# P10 round loop for robustness; P2 k-step second-half LDS fragment reads hoisted into first-half MFMA run
# speedup vs baseline: 1.0492x; 1.0054x over previous
.Lq_round:
	s_mov_b32 s12, 0
	s_mov_b32 s14, s101

.Lq_vnext:
	s_add_i32 s14, s14, s26
	s_add_u32 s13, s13, 0x200
	s_add_u32 s100, s100, 1
	s_cmp_le_u32 s100, s12
	s_cbranch_scc1 .Lq_vtok
	s_add_i32 s8, s8, 1
	s_cmp_lt_u32 s8, 16
	s_cbranch_scc1 .Lq_vpass
	s_waitcnt vmcnt(0)
	s_mov_b32 s8, s12
	s_cmp_lg_u32 s3, 0
	s_cbranch_scc1 .Lq_rnext
	v_mov_b32_e32 v0, 0x120a0
	ds_read_b64 v[0:1], v0
	s_waitcnt lgkmcnt(0)
	v_readfirstlane_b32 s4, v0
	v_readfirstlane_b32 s5, v1
	s_load_dwordx2 s[12:13], s[4:5], 0x30
	s_mov_b32 s14, s101
	s_add_i32 s5, s2, 1
	s_lshl_b32 s4, s5, 12
	s_mul_i32 s5, s5, 0x36000
	s_add_u32 s5, s5, 0x388e0000
	s_mov_b32 s21, 0
	s_waitcnt lgkmcnt(0)
	s_add_u32 s12, s12, s4
	s_addc_u32 s13, s13, 0
.Lq_nitem:
	s_lshl_b32 s20, s14, 2
	s_add_u32 s20, s20, s15
	s_lshl_b32 s1, s20, 12
	v_add_u32_e32 v120, s1, v205
	global_load_dwordx4 v[0:3], v120, s[6:7]
	global_load_dwordx4 v[4:7], v120, s[6:7] offset:16
	global_load_dwordx4 v[8:11], v120, s[6:7] offset:32
	global_load_dwordx4 v[12:15], v120, s[6:7] offset:48
	s_lshr_b32 s0, s20, 12
	s_cmp_ge_u32 s20, 0x8000
	s_cselect_b32 s0, 8, s0
	s_mul_i32 s0, s0, 0x6000
	s_add_u32 s0, s0, s5
	v_add_u32_e32 v121, s0, v205
	global_load_dwordx4 v[16:19], v121, s[6:7]
	global_load_dwordx4 v[20:23], v121, s[6:7] offset:16
	global_load_dwordx4 v[24:27], v121, s[6:7] offset:32
	global_load_dwordx4 v[28:31], v121, s[6:7] offset:48
	v_add_u32_e32 v122, 0x1000, v121
	global_load_dwordx4 v[32:35], v122, s[6:7]
	global_load_dwordx4 v[36:39], v122, s[6:7] offset:16
	global_load_dwordx4 v[40:43], v122, s[6:7] offset:32
	global_load_dwordx4 v[44:47], v122, s[6:7] offset:48
	global_load_dwordx4 v[48:51], v205, s[12:13]
	global_load_dwordx4 v[52:55], v205, s[12:13] offset:16
	global_load_dwordx4 v[56:59], v205, s[12:13] offset:32
	global_load_dwordx4 v[60:63], v205, s[12:13] offset:48
	s_waitcnt vmcnt(12)
	v_mul_f32_e32 v64, v0, v0
	v_fmac_f32_e32 v64, v1, v1
	v_fmac_f32_e32 v64, v2, v2
	v_fmac_f32_e32 v64, v3, v3
	v_fmac_f32_e32 v64, v4, v4
	v_fmac_f32_e32 v64, v5, v5
	v_fmac_f32_e32 v64, v6, v6
	v_fmac_f32_e32 v64, v7, v7
	v_fmac_f32_e32 v64, v8, v8
	v_fmac_f32_e32 v64, v9, v9
	v_fmac_f32_e32 v64, v10, v10
	v_fmac_f32_e32 v64, v11, v11
	v_fmac_f32_e32 v64, v12, v12
	v_fmac_f32_e32 v64, v13, v13
	v_fmac_f32_e32 v64, v14, v14
	v_fmac_f32_e32 v64, v15, v15
	s_nop 1
	v_add_f32_dpp v65, v64, v64 quad_perm:[1,0,3,2] row_mask:0xf bank_mask:0xf
	s_nop 1
	v_add_f32_dpp v64, v65, v65 quad_perm:[2,3,0,1] row_mask:0xf bank_mask:0xf
	s_nop 1
	v_add_f32_dpp v65, v64, v64 row_half_mirror row_mask:0xf bank_mask:0xf
	s_nop 1
	v_add_f32_dpp v64, v65, v65 row_ror:8 row_mask:0xf bank_mask:0xf
	s_nop 1
	v_readlane_b32 s0, v64, 0
	v_readlane_b32 s1, v64, 16
	v_readlane_b32 s4, v64, 32
	v_readlane_b32 s100, v64, 48
	v_mov_b32_e32 v65, s0
	v_add_f32_e32 v65, s1, v65
	v_add_f32_e32 v65, s4, v65
	v_add_f32_e32 v65, s100, v65
	v_mov_b32_e32 v66, 0x358637bd
	v_fmac_f32_e32 v66, 0x3a800000, v65
	v_rsq_f32_e32 v66, v66
	s_waitcnt vmcnt(0)
	v_mul_f32_e32 v0, v0, v66
	v_add_f32_e32 v32, 1.0, v32
	v_mul_f32_e32 v0, v0, v48
	v_fma_f32 v0, v0, v32, v16
	v_mul_f32_e32 v1, v1, v66
	v_add_f32_e32 v33, 1.0, v33
	v_mul_f32_e32 v1, v1, v49
	v_fma_f32 v1, v1, v33, v17
	v_mul_f32_e32 v2, v2, v66
	v_add_f32_e32 v34, 1.0, v34
	v_mul_f32_e32 v2, v2, v50
	v_fma_f32 v2, v2, v34, v18
	v_mul_f32_e32 v3, v3, v66
	v_add_f32_e32 v35, 1.0, v35
	v_mul_f32_e32 v3, v3, v51
	v_fma_f32 v3, v3, v35, v19
	v_mul_f32_e32 v4, v4, v66
	v_add_f32_e32 v36, 1.0, v36
	v_mul_f32_e32 v4, v4, v52
	v_fma_f32 v4, v4, v36, v20
	v_mul_f32_e32 v5, v5, v66
	v_add_f32_e32 v37, 1.0, v37
	v_mul_f32_e32 v5, v5, v53
	v_fma_f32 v5, v5, v37, v21
	v_mul_f32_e32 v6, v6, v66
	v_add_f32_e32 v38, 1.0, v38
	v_mul_f32_e32 v6, v6, v54
	v_fma_f32 v6, v6, v38, v22
	v_mul_f32_e32 v7, v7, v66
	v_add_f32_e32 v39, 1.0, v39
	v_mul_f32_e32 v7, v7, v55
	v_fma_f32 v7, v7, v39, v23
	v_mul_f32_e32 v8, v8, v66
	v_add_f32_e32 v40, 1.0, v40
	v_mul_f32_e32 v8, v8, v56
	v_fma_f32 v8, v8, v40, v24
	v_mul_f32_e32 v9, v9, v66
	v_add_f32_e32 v41, 1.0, v41
	v_mul_f32_e32 v9, v9, v57
	v_fma_f32 v9, v9, v41, v25
	v_mul_f32_e32 v10, v10, v66
	v_add_f32_e32 v42, 1.0, v42
	v_mul_f32_e32 v10, v10, v58
	v_fma_f32 v10, v10, v42, v26
	v_mul_f32_e32 v11, v11, v66
	v_add_f32_e32 v43, 1.0, v43
	v_mul_f32_e32 v11, v11, v59
	v_fma_f32 v11, v11, v43, v27
	v_mul_f32_e32 v12, v12, v66
	v_add_f32_e32 v44, 1.0, v44
	v_mul_f32_e32 v12, v12, v60
	v_fma_f32 v12, v12, v44, v28
	v_mul_f32_e32 v13, v13, v66
	v_add_f32_e32 v45, 1.0, v45
	v_mul_f32_e32 v13, v13, v61
	v_fma_f32 v13, v13, v45, v29
	v_mul_f32_e32 v14, v14, v66
	v_add_f32_e32 v46, 1.0, v46
	v_mul_f32_e32 v14, v14, v62
	v_fma_f32 v14, v14, v46, v30
	v_mul_f32_e32 v15, v15, v66
	v_add_f32_e32 v47, 1.0, v47
	v_mul_f32_e32 v15, v15, v63
	v_fma_f32 v15, v15, v47, v31
	v_cvt_pk_bf16_f32 v0, v0, v1
	v_cvt_pk_bf16_f32 v1, v2, v3
	v_cvt_pk_bf16_f32 v2, v4, v5
	v_cvt_pk_bf16_f32 v3, v6, v7
	v_cvt_pk_bf16_f32 v4, v8, v9
	v_cvt_pk_bf16_f32 v5, v10, v11
	v_cvt_pk_bf16_f32 v6, v12, v13
	v_cvt_pk_bf16_f32 v7, v14, v15
	s_lshl_b32 s1, s20, 11
	s_add_u32 s1, s1, 0x8800000
	v_add_u32_e32 v120, s1, v206
	global_store_dwordx4 v120, v[0:3], s[6:7]
	global_store_dwordx4 v120, v[4:7], s[6:7] offset:16
	s_add_i32 s14, s14, s26
	s_add_u32 s21, s21, 1
	s_cmp_lt_u32 s21, s8
	s_cbranch_scc1 .Lq_nitem
.Lq_rnext:
	s_waitcnt vmcnt(0) lgkmcnt(0)
	s_mul_i32 s0, s26, 17
	s_add_i32 s101, s101, s0
	s_cmp_lt_i32 s101, s9
	s_cbranch_scc1 .Lq_round

.LBB0_313:
	s_mul_hi_i32 s0, s2, 0x2aaaaaab
	s_lshr_b32 s1, s0, 31
	s_ashr_i32 s0, s0, 3
	s_add_i32 s0, s0, s1
	s_mul_i32 s1, s0, 0xffffffd0
	s_add_i32 s4, s2, s1
	s_ashr_i32 s1, s0, 31
	v_mov_b32_e32 v98, v211
	s_lshl_b64 s[6:7], s[0:1], 18
	s_add_u32 s6, s30, s6
	v_ashrrev_i32_e32 v96, 3, v98
	v_ashrrev_i32_e32 v97, 31, v96
	s_addc_u32 s7, s31, s7
	v_lshlrev_b64 v[0:1], 11, v[96:97]
	v_lshlrev_b32_e32 v4, 4, v98
	v_lshl_add_u64 v[2:3], s[6:7], 0, v[0:1]
	v_and_b32_e32 v208, 0x70, v4
	v_lshl_add_u64 v[134:135], v[2:3], 0, v[208:209]
	v_add_co_u32_e32 v128, vcc, s9, v134
	s_ashr_i32 s5, s4, 31
	s_nop 0
	v_addc_co_u32_e32 v129, vcc, 0, v135, vcc
	s_lshl_b64 s[4:5], s[4:5], 18
	v_add_co_u32_e32 v130, vcc, s8, v134
	s_add_u32 s4, s46, s4
	s_nop 0
	v_addc_co_u32_e32 v131, vcc, 0, v135, vcc
	s_addc_u32 s5, s47, s5
	v_add_co_u32_e32 v132, vcc, s10, v134
	v_lshl_add_u64 v[0:1], s[4:5], 0, v[0:1]
	s_nop 0
	v_addc_co_u32_e32 v133, vcc, 0, v135, vcc
	v_lshl_add_u64 v[120:121], v[0:1], 0, v[208:209]
	global_load_dwordx4 v[0:3], v[134:135], off
	global_load_dwordx4 v[4:7], v[128:129], off
	global_load_dwordx4 v[8:11], v[130:131], off
	global_load_dwordx4 v[12:15], v[132:133], off
	global_load_dwordx4 v[16:19], v[120:121], off
	v_add_co_u32_e32 v122, vcc, s9, v120
	v_mul_u32_u24_e32 v96, 0xa0, v96
	s_nop 0
	v_addc_co_u32_e32 v123, vcc, 0, v121, vcc
	v_add_co_u32_e32 v124, vcc, s8, v120
	global_load_dwordx4 v[20:23], v[122:123], off
	s_nop 0
	v_addc_co_u32_e32 v125, vcc, 0, v121, vcc
	global_load_dwordx4 v[24:27], v[124:125], off
	v_add_co_u32_e32 v126, vcc, s10, v120
	v_add3_u32 v136, 0, v96, v208
	s_nop 0
	v_addc_co_u32_e32 v127, vcc, 0, v121, vcc
	global_load_dwordx4 v[28:31], v[126:127], off
	global_load_dwordx4 v[92:95], v[134:135], off offset:128
	global_load_dwordx4 v[80:83], v[128:129], off offset:128
	global_load_dwordx4 v[84:87], v[130:131], off offset:128
	global_load_dwordx4 v[88:91], v[132:133], off offset:128
	global_load_dwordx4 v[68:71], v[120:121], off offset:128
	global_load_dwordx4 v[72:75], v[122:123], off offset:128
	global_load_dwordx4 v[76:79], v[124:125], off offset:128
	global_load_dwordx4 v[64:67], v[126:127], off offset:128
	global_load_dwordx4 v[60:63], v[134:135], off offset:256
	global_load_dwordx4 v[48:51], v[128:129], off offset:256
	global_load_dwordx4 v[52:55], v[130:131], off offset:256
	global_load_dwordx4 v[56:59], v[132:133], off offset:256
	global_load_dwordx4 v[36:39], v[120:121], off offset:256
	global_load_dwordx4 v[40:43], v[122:123], off offset:256
	global_load_dwordx4 v[44:47], v[124:125], off offset:256
	global_load_dwordx4 v[32:35], v[126:127], off offset:256
	s_barrier
	v_and_b32_e32 v96, 15, v98
	v_lshrrev_b32_e32 v97, 1, v98
	v_and_or_b32 v96, v97, s43, v96
	v_mul_u32_u24_e32 v96, 0xa0, v96
	v_and_b32_e32 v97, 48, v98
	v_add3_u32 v137, 0, v96, v97
	v_and_b32_e32 v96, 0x4f, v98
	v_mul_u32_u24_e32 v96, 0x50, v96
	v_lshlrev_b32_e32 v96, 1, v96
	v_add3_u32 v138, 0, v96, v97
	v_add_u32_e32 v138, 0x5000, v138
	v_add_u32_e32 v139, 0xf000, v136
	s_mul_hi_i32 s4, s0, 0x180000
	s_mul_i32 s5, s0, 0x180000
	s_mulk_i32 s0, 0xe800
	s_add_i32 s0, s3, s0
	s_ashr_i32 s1, s0, 31
	s_add_u32 s5, s20, s5
	s_addc_u32 s4, s21, s4
	s_lshl_b64 s[0:1], s[0:1], 1
	s_add_u32 s0, s5, s0
	s_addc_u32 s1, s4, s1
	s_add_i32 s2, s2, s26
	s_add_i32 s3, s3, s18
	s_cmpk_gt_i32 s2, 0x32ff
	s_waitcnt vmcnt(23)
	ds_write_b128 v136, v[0:3]
	s_waitcnt vmcnt(22)
	ds_write_b128 v136, v[4:7] offset:5120
	s_waitcnt vmcnt(21)
	ds_write_b128 v136, v[8:11] offset:10240
	s_waitcnt vmcnt(20)
	ds_write_b128 v136, v[12:15] offset:15360
	s_waitcnt vmcnt(19)
	ds_write_b128 v136, v[16:19] offset:20480
	s_waitcnt vmcnt(18)
	ds_write_b128 v136, v[20:23] offset:25600
	s_waitcnt vmcnt(17)
	ds_write_b128 v136, v[24:27] offset:30720
	s_waitcnt vmcnt(16)
	ds_write_b128 v136, v[28:31] offset:35840
	global_load_dwordx4 v[0:3], v[126:127], off offset:384
	global_load_dwordx4 v[4:7], v[124:125], off offset:384
	global_load_dwordx4 v[8:11], v[122:123], off offset:384
	global_load_dwordx4 v[12:15], v[120:121], off offset:384
	global_load_dwordx4 v[16:19], v[132:133], off offset:384
	global_load_dwordx4 v[20:23], v[130:131], off offset:384
	global_load_dwordx4 v[24:27], v[128:129], off offset:384
	global_load_dwordx4 v[28:31], v[134:135], off offset:384
	s_waitcnt lgkmcnt(0)
	s_barrier
	ds_read_b128 v[96:99], v137
	ds_read_b128 v[100:103], v137 offset:2560
	ds_read_b128 v[104:107], v137 offset:5120
	ds_read_b128 v[108:111], v137 offset:7680
	ds_read_b128 v[112:115], v138
	ds_read_b128 v[116:119], v138 offset:2560
	ds_read_b128 v[140:143], v138 offset:5120
	ds_read_b128 v[144:147], v138 offset:7680
	s_waitcnt lgkmcnt(3)
	v_mfma_f32_16x16x32_bf16 v[148:151], v[96:99], v[112:115], 0
	s_waitcnt lgkmcnt(2)
	v_mfma_f32_16x16x32_bf16 v[152:155], v[96:99], v[116:119], 0
	s_waitcnt lgkmcnt(1)
	v_mfma_f32_16x16x32_bf16 v[156:159], v[96:99], v[140:143], 0
	s_waitcnt lgkmcnt(0)
	v_mfma_f32_16x16x32_bf16 v[96:99], v[96:99], v[144:147], 0
	ds_read_b128 v[184:187], v137 offset:2624
	ds_read_b128 v[188:191], v137 offset:5184
	ds_read_b128 v[192:195], v137 offset:7744
	ds_read_b128 v[196:199], v138 offset:64
	ds_read_b128 v[200:203], v138 offset:2624
	ds_read_b128 v[204:207], v138 offset:5184
	ds_read_b128 v[212:215], v138 offset:7744
	v_mfma_f32_16x16x32_bf16 v[160:163], v[100:103], v[112:115], 0
	v_mfma_f32_16x16x32_bf16 v[164:167], v[100:103], v[116:119], 0
	v_mfma_f32_16x16x32_bf16 v[168:171], v[100:103], v[140:143], 0
	v_mfma_f32_16x16x32_bf16 v[100:103], v[100:103], v[144:147], 0
	v_mfma_f32_16x16x32_bf16 v[172:175], v[104:107], v[112:115], 0
	v_mfma_f32_16x16x32_bf16 v[176:179], v[104:107], v[116:119], 0
	v_mfma_f32_16x16x32_bf16 v[180:183], v[104:107], v[140:143], 0
	v_mfma_f32_16x16x32_bf16 v[104:107], v[104:107], v[144:147], 0
	v_mfma_f32_16x16x32_bf16 v[112:115], v[108:111], v[112:115], 0
	v_mfma_f32_16x16x32_bf16 v[116:119], v[108:111], v[116:119], 0
	v_mfma_f32_16x16x32_bf16 v[140:143], v[108:111], v[140:143], 0
	v_mfma_f32_16x16x32_bf16 v[108:111], v[108:111], v[144:147], 0
	ds_read_b128 v[144:147], v137 offset:64
	s_waitcnt vmcnt(23)
	ds_write_b128 v136, v[92:95] offset:40960
	s_waitcnt vmcnt(22)
	ds_write_b128 v136, v[80:83] offset:46080
	s_waitcnt vmcnt(21)
	ds_write_b128 v136, v[84:87] offset:51200
	s_waitcnt vmcnt(20)
	ds_write_b128 v136, v[88:91] offset:56320
	s_waitcnt vmcnt(19)
	ds_write_b128 v136, v[68:71] offset:61440
	s_waitcnt vmcnt(18)
	ds_write_b128 v139, v[72:75] offset:5120
	s_waitcnt vmcnt(17)
	ds_write_b128 v139, v[76:79] offset:10240
	s_waitcnt vmcnt(16)
	ds_write_b128 v139, v[64:67] offset:15360
	s_waitcnt lgkmcnt(8)
	v_mfma_f32_16x16x32_bf16 v[148:151], v[144:147], v[196:199], v[148:151]
	s_waitcnt lgkmcnt(10)
	v_mfma_f32_16x16x32_bf16 v[152:155], v[144:147], v[200:203], v[152:155]
	s_waitcnt lgkmcnt(9)
	v_mfma_f32_16x16x32_bf16 v[156:159], v[144:147], v[204:207], v[156:159]
	s_waitcnt lgkmcnt(8)
	v_mfma_f32_16x16x32_bf16 v[144:147], v[144:147], v[212:215], v[96:99]
	v_mfma_f32_16x16x32_bf16 v[160:163], v[184:187], v[196:199], v[160:163]
	v_mfma_f32_16x16x32_bf16 v[164:167], v[184:187], v[200:203], v[164:167]
	v_mfma_f32_16x16x32_bf16 v[168:171], v[184:187], v[204:207], v[168:171]
	v_mfma_f32_16x16x32_bf16 v[184:187], v[184:187], v[212:215], v[100:103]
	v_mfma_f32_16x16x32_bf16 v[172:175], v[188:191], v[196:199], v[172:175]
	v_mfma_f32_16x16x32_bf16 v[176:179], v[188:191], v[200:203], v[176:179]
	v_mfma_f32_16x16x32_bf16 v[180:183], v[188:191], v[204:207], v[180:183]
	v_mfma_f32_16x16x32_bf16 v[188:191], v[188:191], v[212:215], v[104:107]
	v_mfma_f32_16x16x32_bf16 v[196:199], v[192:195], v[196:199], v[112:115]
	v_mfma_f32_16x16x32_bf16 v[116:119], v[192:195], v[200:203], v[116:119]
	v_mfma_f32_16x16x32_bf16 v[140:143], v[192:195], v[204:207], v[140:143]
	v_mfma_f32_16x16x32_bf16 v[192:195], v[192:195], v[212:215], v[108:111]
	global_load_dwordx4 v[68:71], v[134:135], off offset:512
	global_load_dwordx4 v[88:91], v[128:129], off offset:512
	global_load_dwordx4 v[92:95], v[130:131], off offset:512
	global_load_dwordx4 v[96:99], v[132:133], off offset:512
	global_load_dwordx4 v[100:103], v[120:121], off offset:512
	global_load_dwordx4 v[104:107], v[122:123], off offset:512
	global_load_dwordx4 v[108:111], v[124:125], off offset:512
	global_load_dwordx4 v[112:115], v[126:127], off offset:512
	s_waitcnt lgkmcnt(0)
	s_barrier
	ds_read_b128 v[64:67], v137 offset:40960
	ds_read_b128 v[72:75], v137 offset:43520
	ds_read_b128 v[76:79], v137 offset:46080
	ds_read_b128 v[80:83], v137 offset:48640
	ds_read_b128 v[84:87], v138 offset:40960
	ds_read_b128 v[200:203], v138 offset:43520
	ds_read_b128 v[204:207], v138 offset:46080
	ds_read_b128 v[212:215], v138 offset:48640
	s_waitcnt lgkmcnt(3)
	v_mfma_f32_16x16x32_bf16 v[148:151], v[64:67], v[84:87], v[148:151]
	s_waitcnt lgkmcnt(2)
	v_mfma_f32_16x16x32_bf16 v[152:155], v[64:67], v[200:203], v[152:155]
	s_waitcnt lgkmcnt(1)
	v_mfma_f32_16x16x32_bf16 v[156:159], v[64:67], v[204:207], v[156:159]
	s_waitcnt lgkmcnt(0)
	v_mfma_f32_16x16x32_bf16 v[64:67], v[64:67], v[212:215], v[144:147]
	v_mfma_f32_16x16x32_bf16 v[144:147], v[72:75], v[84:87], v[160:163]
	v_mfma_f32_16x16x32_bf16 v[160:163], v[72:75], v[200:203], v[164:167]
	v_mfma_f32_16x16x32_bf16 v[164:167], v[72:75], v[204:207], v[168:171]
	v_mfma_f32_16x16x32_bf16 v[72:75], v[72:75], v[212:215], v[184:187]
	ds_read_b128 v[184:187], v137 offset:43584
	v_mfma_f32_16x16x32_bf16 v[168:171], v[76:79], v[84:87], v[172:175]
	v_mfma_f32_16x16x32_bf16 v[172:175], v[76:79], v[200:203], v[176:179]
	v_mfma_f32_16x16x32_bf16 v[176:179], v[76:79], v[204:207], v[180:183]
	ds_read_b128 v[180:183], v137 offset:41024
	v_mfma_f32_16x16x32_bf16 v[76:79], v[76:79], v[212:215], v[188:191]
	ds_read_b128 v[188:191], v137 offset:46144
	v_mfma_f32_16x16x32_bf16 v[84:87], v[80:83], v[84:87], v[196:199]
	ds_read_b128 v[196:199], v138 offset:41024
	v_mfma_f32_16x16x32_bf16 v[116:119], v[80:83], v[200:203], v[116:119]
	ds_read_b128 v[200:203], v138 offset:43584
	v_mfma_f32_16x16x32_bf16 v[140:143], v[80:83], v[204:207], v[140:143]
	ds_read_b128 v[204:207], v138 offset:46144
	v_mfma_f32_16x16x32_bf16 v[80:83], v[80:83], v[212:215], v[192:195]
	ds_read_b128 v[192:195], v137 offset:48704
	ds_read_b128 v[212:215], v138 offset:48704
	s_waitcnt vmcnt(23)
	ds_write_b128 v136, v[60:63]
	s_waitcnt vmcnt(22)
	ds_write_b128 v136, v[48:51] offset:5120
	s_waitcnt vmcnt(21)
	ds_write_b128 v136, v[52:55] offset:10240
	s_waitcnt vmcnt(20)
	ds_write_b128 v136, v[56:59] offset:15360
	s_waitcnt vmcnt(19)
	ds_write_b128 v136, v[36:39] offset:20480
	s_waitcnt vmcnt(18)
	ds_write_b128 v136, v[40:43] offset:25600
	s_waitcnt vmcnt(17)
	ds_write_b128 v136, v[44:47] offset:30720
	s_waitcnt vmcnt(16)
	ds_write_b128 v136, v[32:35] offset:35840
	s_waitcnt lgkmcnt(8)
	v_mfma_f32_16x16x32_bf16 v[148:151], v[180:183], v[196:199], v[148:151]
	s_waitcnt lgkmcnt(10)
	v_mfma_f32_16x16x32_bf16 v[152:155], v[180:183], v[200:203], v[152:155]
	s_waitcnt lgkmcnt(9)
	v_mfma_f32_16x16x32_bf16 v[156:159], v[180:183], v[204:207], v[156:159]
	s_waitcnt lgkmcnt(8)
	v_mfma_f32_16x16x32_bf16 v[64:67], v[180:183], v[212:215], v[64:67]
	v_mfma_f32_16x16x32_bf16 v[144:147], v[184:187], v[196:199], v[144:147]
	v_mfma_f32_16x16x32_bf16 v[160:163], v[184:187], v[200:203], v[160:163]
	v_mfma_f32_16x16x32_bf16 v[164:167], v[184:187], v[204:207], v[164:167]
	v_mfma_f32_16x16x32_bf16 v[180:183], v[184:187], v[212:215], v[72:75]
	v_mfma_f32_16x16x32_bf16 v[168:171], v[188:191], v[196:199], v[168:171]
	v_mfma_f32_16x16x32_bf16 v[172:175], v[188:191], v[200:203], v[172:175]
	v_mfma_f32_16x16x32_bf16 v[176:179], v[188:191], v[204:207], v[176:179]
	v_mfma_f32_16x16x32_bf16 v[184:187], v[188:191], v[212:215], v[76:79]
	global_load_dwordx4 v[32:35], v[134:135], off offset:640
	global_load_dwordx4 v[36:39], v[128:129], off offset:640
	global_load_dwordx4 v[40:43], v[130:131], off offset:640
	global_load_dwordx4 v[44:47], v[132:133], off offset:640
	global_load_dwordx4 v[48:51], v[120:121], off offset:640
	global_load_dwordx4 v[72:75], v[122:123], off offset:640
	global_load_dwordx4 v[76:79], v[124:125], off offset:640
	global_load_dwordx4 v[60:63], v[126:127], off offset:640
	s_waitcnt lgkmcnt(0)
	s_barrier
	v_mfma_f32_16x16x32_bf16 v[84:87], v[192:195], v[196:199], v[84:87]
	v_mfma_f32_16x16x32_bf16 v[116:119], v[192:195], v[200:203], v[116:119]
	v_mfma_f32_16x16x32_bf16 v[140:143], v[192:195], v[204:207], v[140:143]
	v_mfma_f32_16x16x32_bf16 v[80:83], v[192:195], v[212:215], v[80:83]
	ds_read_b128 v[52:55], v137
	ds_read_b128 v[56:59], v137 offset:2560
	ds_read_b128 v[188:191], v137 offset:5120
	ds_read_b128 v[192:195], v137 offset:7680
	ds_read_b128 v[196:199], v138
	ds_read_b128 v[200:203], v138 offset:2560
	ds_read_b128 v[204:207], v138 offset:5120
	ds_read_b128 v[212:215], v138 offset:7680
	s_waitcnt lgkmcnt(3)
	v_mfma_f32_16x16x32_bf16 v[148:151], v[52:55], v[196:199], v[148:151]
	s_waitcnt lgkmcnt(2)
	v_mfma_f32_16x16x32_bf16 v[152:155], v[52:55], v[200:203], v[152:155]
	s_waitcnt lgkmcnt(1)
	v_mfma_f32_16x16x32_bf16 v[156:159], v[52:55], v[204:207], v[156:159]
	s_waitcnt lgkmcnt(0)
	v_mfma_f32_16x16x32_bf16 v[52:55], v[52:55], v[212:215], v[64:67]
	v_mfma_f32_16x16x32_bf16 v[64:67], v[56:59], v[196:199], v[144:147]
	v_mfma_f32_16x16x32_bf16 v[144:147], v[56:59], v[200:203], v[160:163]
	v_mfma_f32_16x16x32_bf16 v[160:163], v[56:59], v[204:207], v[164:167]
	v_mfma_f32_16x16x32_bf16 v[56:59], v[56:59], v[212:215], v[180:183]
	ds_read_b128 v[180:183], v137 offset:64
	v_mfma_f32_16x16x32_bf16 v[164:167], v[188:191], v[196:199], v[168:171]
	v_mfma_f32_16x16x32_bf16 v[168:171], v[188:191], v[200:203], v[172:175]
	v_mfma_f32_16x16x32_bf16 v[172:175], v[188:191], v[204:207], v[176:179]
	v_mfma_f32_16x16x32_bf16 v[176:179], v[188:191], v[212:215], v[184:187]
	ds_read_b128 v[184:187], v137 offset:2624
	ds_read_b128 v[188:191], v137 offset:5184
	v_mfma_f32_16x16x32_bf16 v[84:87], v[192:195], v[196:199], v[84:87]
	ds_read_b128 v[196:199], v138 offset:64
	v_mfma_f32_16x16x32_bf16 v[116:119], v[192:195], v[200:203], v[116:119]
	ds_read_b128 v[200:203], v138 offset:2624
	v_mfma_f32_16x16x32_bf16 v[140:143], v[192:195], v[204:207], v[140:143]
	ds_read_b128 v[204:207], v138 offset:5184
	v_mfma_f32_16x16x32_bf16 v[80:83], v[192:195], v[212:215], v[80:83]
	ds_read_b128 v[192:195], v137 offset:7744
	ds_read_b128 v[212:215], v138 offset:7744
	s_waitcnt vmcnt(16)
	ds_write_b128 v136, v[28:31] offset:40960
	ds_write_b128 v136, v[24:27] offset:46080
	ds_write_b128 v136, v[20:23] offset:51200
	ds_write_b128 v136, v[16:19] offset:56320
	ds_write_b128 v136, v[12:15] offset:61440
	ds_write_b128 v139, v[8:11] offset:5120
	ds_write_b128 v139, v[4:7] offset:10240
	ds_write_b128 v139, v[0:3] offset:15360
	s_waitcnt lgkmcnt(8)
	v_mfma_f32_16x16x32_bf16 v[148:151], v[180:183], v[196:199], v[148:151]
	s_waitcnt lgkmcnt(10)
	v_mfma_f32_16x16x32_bf16 v[152:155], v[180:183], v[200:203], v[152:155]
	s_waitcnt lgkmcnt(9)
	v_mfma_f32_16x16x32_bf16 v[156:159], v[180:183], v[204:207], v[156:159]
	s_waitcnt lgkmcnt(8)
	v_mfma_f32_16x16x32_bf16 v[180:183], v[180:183], v[212:215], v[52:55]
	v_mfma_f32_16x16x32_bf16 v[224:227], v[184:187], v[196:199], v[64:67]
	v_mfma_f32_16x16x32_bf16 v[144:147], v[184:187], v[200:203], v[144:147]
	v_mfma_f32_16x16x32_bf16 v[160:163], v[184:187], v[204:207], v[160:163]
	v_mfma_f32_16x16x32_bf16 v[56:59], v[184:187], v[212:215], v[56:59]
	v_mfma_f32_16x16x32_bf16 v[164:167], v[188:191], v[196:199], v[164:167]
	v_mfma_f32_16x16x32_bf16 v[168:171], v[188:191], v[200:203], v[168:171]
	v_mfma_f32_16x16x32_bf16 v[172:175], v[188:191], v[204:207], v[172:175]
	v_mfma_f32_16x16x32_bf16 v[176:179], v[188:191], v[212:215], v[176:179]
	v_mfma_f32_16x16x32_bf16 v[184:187], v[192:195], v[196:199], v[84:87]
	v_mfma_f32_16x16x32_bf16 v[188:191], v[192:195], v[212:215], v[80:83]
	global_load_dwordx4 v[4:7], v[134:135], off offset:768
	global_load_dwordx4 v[8:11], v[128:129], off offset:768
	global_load_dwordx4 v[16:19], v[130:131], off offset:768
	global_load_dwordx4 v[24:27], v[132:133], off offset:768
	global_load_dwordx4 v[52:55], v[120:121], off offset:768
	global_load_dwordx4 v[80:83], v[122:123], off offset:768
	global_load_dwordx4 v[84:87], v[124:125], off offset:768
	global_load_dwordx4 v[64:67], v[126:127], off offset:768
	s_waitcnt lgkmcnt(0)
	s_barrier
	v_mfma_f32_16x16x32_bf16 v[116:119], v[192:195], v[200:203], v[116:119]
	v_mfma_f32_16x16x32_bf16 v[140:143], v[192:195], v[204:207], v[140:143]
	ds_read_b128 v[0:3], v137 offset:40960
	ds_read_b128 v[12:15], v137 offset:43520
	ds_read_b128 v[20:23], v137 offset:46080
	ds_read_b128 v[28:31], v137 offset:48640
	ds_read_b128 v[192:195], v138 offset:40960
	ds_read_b128 v[196:199], v138 offset:43520
	ds_read_b128 v[200:203], v138 offset:46080
	ds_read_b128 v[204:207], v138 offset:48640
	s_waitcnt lgkmcnt(3)
	v_mfma_f32_16x16x32_bf16 v[148:151], v[0:3], v[192:195], v[148:151]
	s_waitcnt lgkmcnt(2)
	v_mfma_f32_16x16x32_bf16 v[152:155], v[0:3], v[196:199], v[152:155]
	s_waitcnt lgkmcnt(1)
	v_mfma_f32_16x16x32_bf16 v[156:159], v[0:3], v[200:203], v[156:159]
	s_waitcnt lgkmcnt(0)
	v_mfma_f32_16x16x32_bf16 v[0:3], v[0:3], v[204:207], v[180:183]
	ds_read_b128 v[212:215], v138 offset:48704
	v_mfma_f32_16x16x32_bf16 v[180:183], v[12:15], v[192:195], v[224:227]
	v_mfma_f32_16x16x32_bf16 v[144:147], v[12:15], v[196:199], v[144:147]
	v_mfma_f32_16x16x32_bf16 v[160:163], v[12:15], v[200:203], v[160:163]
	v_mfma_f32_16x16x32_bf16 v[12:15], v[12:15], v[204:207], v[56:59]
	v_mfma_f32_16x16x32_bf16 v[56:59], v[20:23], v[192:195], v[164:167]
	v_mfma_f32_16x16x32_bf16 v[164:167], v[20:23], v[196:199], v[168:171]
	v_mfma_f32_16x16x32_bf16 v[168:171], v[20:23], v[200:203], v[172:175]
	v_mfma_f32_16x16x32_bf16 v[20:23], v[20:23], v[204:207], v[176:179]
	ds_read_b128 v[176:179], v137 offset:41024
	v_mfma_f32_16x16x32_bf16 v[172:175], v[28:31], v[192:195], v[184:187]
	ds_read_b128 v[184:187], v137 offset:43584
	ds_read_b128 v[192:195], v137 offset:48704
	v_mfma_f32_16x16x32_bf16 v[116:119], v[28:31], v[196:199], v[116:119]
	ds_read_b128 v[196:199], v138 offset:41024
	v_mfma_f32_16x16x32_bf16 v[140:143], v[28:31], v[200:203], v[140:143]
	ds_read_b128 v[200:203], v138 offset:43584
	v_mfma_f32_16x16x32_bf16 v[28:31], v[28:31], v[204:207], v[188:191]
	ds_read_b128 v[188:191], v137 offset:46144
	ds_read_b128 v[204:207], v138 offset:46144
	s_nop 0
	s_waitcnt vmcnt(23)
	ds_write_b128 v136, v[68:71]
	s_waitcnt vmcnt(22)
	ds_write_b128 v136, v[88:91] offset:5120
	s_waitcnt vmcnt(21)
	ds_write_b128 v136, v[92:95] offset:10240
	s_waitcnt vmcnt(20)
	ds_write_b128 v136, v[96:99] offset:15360
	s_waitcnt vmcnt(19)
	ds_write_b128 v136, v[100:103] offset:20480
	s_waitcnt vmcnt(18)
	ds_write_b128 v136, v[104:107] offset:25600
	s_waitcnt vmcnt(17)
	ds_write_b128 v136, v[108:111] offset:30720
	s_waitcnt vmcnt(16)
	ds_write_b128 v136, v[112:115] offset:35840
	s_waitcnt lgkmcnt(8)
	v_mfma_f32_16x16x32_bf16 v[148:151], v[176:179], v[196:199], v[148:151]
	s_waitcnt lgkmcnt(10)
	v_mfma_f32_16x16x32_bf16 v[152:155], v[176:179], v[200:203], v[152:155]
	s_waitcnt lgkmcnt(9)
	v_mfma_f32_16x16x32_bf16 v[156:159], v[176:179], v[204:207], v[156:159]
	s_waitcnt lgkmcnt(8)
	v_mfma_f32_16x16x32_bf16 v[176:179], v[176:179], v[212:215], v[0:3]
	v_mfma_f32_16x16x32_bf16 v[180:183], v[184:187], v[196:199], v[180:183]
	v_mfma_f32_16x16x32_bf16 v[144:147], v[184:187], v[200:203], v[144:147]
	v_mfma_f32_16x16x32_bf16 v[160:163], v[184:187], v[204:207], v[160:163]
	v_mfma_f32_16x16x32_bf16 v[184:187], v[184:187], v[212:215], v[12:15]
	v_mfma_f32_16x16x32_bf16 v[224:227], v[188:191], v[196:199], v[56:59]
	v_mfma_f32_16x16x32_bf16 v[164:167], v[188:191], v[200:203], v[164:167]
	v_mfma_f32_16x16x32_bf16 v[168:171], v[188:191], v[204:207], v[168:171]
	v_mfma_f32_16x16x32_bf16 v[188:191], v[188:191], v[212:215], v[20:23]
	v_mfma_f32_16x16x32_bf16 v[172:175], v[192:195], v[196:199], v[172:175]
	v_mfma_f32_16x16x32_bf16 v[116:119], v[192:195], v[200:203], v[116:119]
	v_mfma_f32_16x16x32_bf16 v[140:143], v[192:195], v[204:207], v[140:143]
	v_mfma_f32_16x16x32_bf16 v[192:195], v[192:195], v[212:215], v[28:31]
	global_load_dwordx4 v[0:3], v[134:135], off offset:896
	global_load_dwordx4 v[12:15], v[128:129], off offset:896
	global_load_dwordx4 v[20:23], v[130:131], off offset:896
	global_load_dwordx4 v[28:31], v[132:133], off offset:896
	global_load_dwordx4 v[56:59], v[120:121], off offset:896
	global_load_dwordx4 v[88:91], v[122:123], off offset:896
	global_load_dwordx4 v[92:95], v[124:125], off offset:896
	global_load_dwordx4 v[68:71], v[126:127], off offset:896
	s_waitcnt lgkmcnt(0)
	s_barrier
	ds_read_b128 v[96:99], v137
	ds_read_b128 v[100:103], v137 offset:2560
	ds_read_b128 v[104:107], v137 offset:5120
	ds_read_b128 v[108:111], v137 offset:7680
	ds_read_b128 v[112:115], v138
	ds_read_b128 v[196:199], v138 offset:2560
	ds_read_b128 v[200:203], v138 offset:5120
	ds_read_b128 v[204:207], v138 offset:7680
	s_waitcnt lgkmcnt(3)
	v_mfma_f32_16x16x32_bf16 v[148:151], v[96:99], v[112:115], v[148:151]
	s_waitcnt lgkmcnt(2)
	v_mfma_f32_16x16x32_bf16 v[152:155], v[96:99], v[196:199], v[152:155]
	s_waitcnt lgkmcnt(1)
	v_mfma_f32_16x16x32_bf16 v[156:159], v[96:99], v[200:203], v[156:159]
	s_waitcnt lgkmcnt(0)
	v_mfma_f32_16x16x32_bf16 v[96:99], v[96:99], v[204:207], v[176:179]
	ds_read_b128 v[212:215], v138 offset:7744
	v_mfma_f32_16x16x32_bf16 v[176:179], v[100:103], v[112:115], v[180:183]
	v_mfma_f32_16x16x32_bf16 v[144:147], v[100:103], v[196:199], v[144:147]
	v_mfma_f32_16x16x32_bf16 v[160:163], v[100:103], v[200:203], v[160:163]
	v_mfma_f32_16x16x32_bf16 v[100:103], v[100:103], v[204:207], v[184:187]
	ds_read_b128 v[184:187], v137 offset:2624
	v_mfma_f32_16x16x32_bf16 v[180:183], v[104:107], v[112:115], v[224:227]
	v_mfma_f32_16x16x32_bf16 v[164:167], v[104:107], v[196:199], v[164:167]
	v_mfma_f32_16x16x32_bf16 v[168:171], v[104:107], v[200:203], v[168:171]
	v_mfma_f32_16x16x32_bf16 v[104:107], v[104:107], v[204:207], v[188:191]
	ds_read_b128 v[188:191], v137 offset:5184
	v_mfma_f32_16x16x32_bf16 v[112:115], v[108:111], v[112:115], v[172:175]
	ds_read_b128 v[172:175], v137 offset:64
	v_mfma_f32_16x16x32_bf16 v[116:119], v[108:111], v[196:199], v[116:119]
	ds_read_b128 v[196:199], v138 offset:64
	v_mfma_f32_16x16x32_bf16 v[140:143], v[108:111], v[200:203], v[140:143]
	ds_read_b128 v[200:203], v138 offset:2624
	v_mfma_f32_16x16x32_bf16 v[108:111], v[108:111], v[204:207], v[192:195]
	ds_read_b128 v[192:195], v137 offset:7744
	ds_read_b128 v[204:207], v138 offset:5184
	s_waitcnt vmcnt(23)
	ds_write_b128 v136, v[32:35] offset:40960
	s_waitcnt vmcnt(22)
	ds_write_b128 v136, v[36:39] offset:46080
	s_waitcnt vmcnt(21)
	ds_write_b128 v136, v[40:43] offset:51200
	s_waitcnt vmcnt(20)
	ds_write_b128 v136, v[44:47] offset:56320
	s_waitcnt vmcnt(19)
	ds_write_b128 v136, v[48:51] offset:61440
	s_waitcnt vmcnt(18)
	ds_write_b128 v139, v[72:75] offset:5120
	s_waitcnt vmcnt(17)
	ds_write_b128 v139, v[76:79] offset:10240
	s_waitcnt vmcnt(16)
	ds_write_b128 v139, v[60:63] offset:15360
	s_waitcnt lgkmcnt(8)
	v_mfma_f32_16x16x32_bf16 v[148:151], v[172:175], v[196:199], v[148:151]
	s_waitcnt lgkmcnt(10)
	v_mfma_f32_16x16x32_bf16 v[152:155], v[172:175], v[200:203], v[152:155]
	s_waitcnt lgkmcnt(9)
	v_mfma_f32_16x16x32_bf16 v[156:159], v[172:175], v[204:207], v[156:159]
	s_waitcnt lgkmcnt(8)
	v_mfma_f32_16x16x32_bf16 v[172:175], v[172:175], v[212:215], v[96:99]
	v_mfma_f32_16x16x32_bf16 v[176:179], v[184:187], v[196:199], v[176:179]
	v_mfma_f32_16x16x32_bf16 v[144:147], v[184:187], v[200:203], v[144:147]
	v_mfma_f32_16x16x32_bf16 v[160:163], v[184:187], v[204:207], v[160:163]
	v_mfma_f32_16x16x32_bf16 v[184:187], v[184:187], v[212:215], v[100:103]
	v_mfma_f32_16x16x32_bf16 v[180:183], v[188:191], v[196:199], v[180:183]
	v_mfma_f32_16x16x32_bf16 v[164:167], v[188:191], v[200:203], v[164:167]
	v_mfma_f32_16x16x32_bf16 v[168:171], v[188:191], v[204:207], v[168:171]
	v_mfma_f32_16x16x32_bf16 v[188:191], v[188:191], v[212:215], v[104:107]
	v_mfma_f32_16x16x32_bf16 v[196:199], v[192:195], v[196:199], v[112:115]
	v_mfma_f32_16x16x32_bf16 v[200:203], v[192:195], v[200:203], v[116:119]
	v_mfma_f32_16x16x32_bf16 v[140:143], v[192:195], v[204:207], v[140:143]
	v_mfma_f32_16x16x32_bf16 v[192:195], v[192:195], v[212:215], v[108:111]
	global_load_dwordx4 v[32:35], v[134:135], off offset:1024
	global_load_dwordx4 v[44:47], v[128:129], off offset:1024
	global_load_dwordx4 v[96:99], v[130:131], off offset:1024
	global_load_dwordx4 v[100:103], v[132:133], off offset:1024
	global_load_dwordx4 v[104:107], v[120:121], off offset:1024
	global_load_dwordx4 v[108:111], v[122:123], off offset:1024
	global_load_dwordx4 v[112:115], v[124:125], off offset:1024
	global_load_dwordx4 v[116:119], v[126:127], off offset:1024
	s_waitcnt lgkmcnt(0)
	s_barrier
	ds_read_b128 v[36:39], v137 offset:40960
	ds_read_b128 v[40:43], v137 offset:43520
	ds_read_b128 v[48:51], v137 offset:46080
	ds_read_b128 v[60:63], v137 offset:48640
	ds_read_b128 v[72:75], v138 offset:40960
	ds_read_b128 v[76:79], v138 offset:43520
	ds_read_b128 v[204:207], v138 offset:46080
	ds_read_b128 v[212:215], v138 offset:48640
	s_waitcnt lgkmcnt(3)
	v_mfma_f32_16x16x32_bf16 v[148:151], v[36:39], v[72:75], v[148:151]
	s_waitcnt lgkmcnt(2)
	v_mfma_f32_16x16x32_bf16 v[152:155], v[36:39], v[76:79], v[152:155]
	s_waitcnt lgkmcnt(1)
	v_mfma_f32_16x16x32_bf16 v[156:159], v[36:39], v[204:207], v[156:159]
	s_waitcnt lgkmcnt(0)
	v_mfma_f32_16x16x32_bf16 v[36:39], v[36:39], v[212:215], v[172:175]
	v_mfma_f32_16x16x32_bf16 v[172:175], v[40:43], v[72:75], v[176:179]
	v_mfma_f32_16x16x32_bf16 v[144:147], v[40:43], v[76:79], v[144:147]
	v_mfma_f32_16x16x32_bf16 v[160:163], v[40:43], v[204:207], v[160:163]
	v_mfma_f32_16x16x32_bf16 v[40:43], v[40:43], v[212:215], v[184:187]
	ds_read_b128 v[184:187], v137 offset:43584
	v_mfma_f32_16x16x32_bf16 v[176:179], v[48:51], v[72:75], v[180:183]
	ds_read_b128 v[180:183], v137 offset:41024
	v_mfma_f32_16x16x32_bf16 v[164:167], v[48:51], v[76:79], v[164:167]
	v_mfma_f32_16x16x32_bf16 v[168:171], v[48:51], v[204:207], v[168:171]
	v_mfma_f32_16x16x32_bf16 v[48:51], v[48:51], v[212:215], v[188:191]
	ds_read_b128 v[188:191], v137 offset:46144
	v_mfma_f32_16x16x32_bf16 v[72:75], v[60:63], v[72:75], v[196:199]
	ds_read_b128 v[196:199], v138 offset:41024
	v_mfma_f32_16x16x32_bf16 v[76:79], v[60:63], v[76:79], v[200:203]
	ds_read_b128 v[200:203], v138 offset:43584
	v_mfma_f32_16x16x32_bf16 v[140:143], v[60:63], v[204:207], v[140:143]
	ds_read_b128 v[204:207], v138 offset:46144
	v_mfma_f32_16x16x32_bf16 v[60:63], v[60:63], v[212:215], v[192:195]
	ds_read_b128 v[192:195], v137 offset:48704
	ds_read_b128 v[212:215], v138 offset:48704
	s_waitcnt vmcnt(23)
	ds_write_b128 v136, v[4:7]
	s_waitcnt vmcnt(22)
	ds_write_b128 v136, v[8:11] offset:5120
	s_waitcnt vmcnt(21)
	ds_write_b128 v136, v[16:19] offset:10240
	s_waitcnt vmcnt(20)
	ds_write_b128 v136, v[24:27] offset:15360
	s_waitcnt vmcnt(19)
	ds_write_b128 v136, v[52:55] offset:20480
	s_waitcnt vmcnt(18)
	ds_write_b128 v136, v[80:83] offset:25600
	s_waitcnt vmcnt(17)
	ds_write_b128 v136, v[84:87] offset:30720
	s_waitcnt vmcnt(16)
	ds_write_b128 v136, v[64:67] offset:35840
	s_waitcnt lgkmcnt(8)
	v_mfma_f32_16x16x32_bf16 v[148:151], v[180:183], v[196:199], v[148:151]
	s_waitcnt lgkmcnt(10)
	v_mfma_f32_16x16x32_bf16 v[152:155], v[180:183], v[200:203], v[152:155]
	s_waitcnt lgkmcnt(9)
	v_mfma_f32_16x16x32_bf16 v[156:159], v[180:183], v[204:207], v[156:159]
	s_waitcnt lgkmcnt(8)
	v_mfma_f32_16x16x32_bf16 v[180:183], v[180:183], v[212:215], v[36:39]
	v_mfma_f32_16x16x32_bf16 v[172:175], v[184:187], v[196:199], v[172:175]
	v_mfma_f32_16x16x32_bf16 v[144:147], v[184:187], v[200:203], v[144:147]
	v_mfma_f32_16x16x32_bf16 v[160:163], v[184:187], v[204:207], v[160:163]
	v_mfma_f32_16x16x32_bf16 v[40:43], v[184:187], v[212:215], v[40:43]
	v_mfma_f32_16x16x32_bf16 v[176:179], v[188:191], v[196:199], v[176:179]
	v_mfma_f32_16x16x32_bf16 v[164:167], v[188:191], v[200:203], v[164:167]
	v_mfma_f32_16x16x32_bf16 v[168:171], v[188:191], v[204:207], v[168:171]
	v_mfma_f32_16x16x32_bf16 v[184:187], v[188:191], v[212:215], v[48:51]
	v_mfma_f32_16x16x32_bf16 v[188:191], v[192:195], v[196:199], v[72:75]
	v_mfma_f32_16x16x32_bf16 v[196:199], v[192:195], v[200:203], v[76:79]
	v_mfma_f32_16x16x32_bf16 v[140:143], v[192:195], v[204:207], v[140:143]
	v_mfma_f32_16x16x32_bf16 v[192:195], v[192:195], v[212:215], v[60:63]
	global_load_dwordx4 v[4:7], v[134:135], off offset:1152
	global_load_dwordx4 v[8:11], v[128:129], off offset:1152
	global_load_dwordx4 v[24:27], v[130:131], off offset:1152
	global_load_dwordx4 v[36:39], v[132:133], off offset:1152
	global_load_dwordx4 v[48:51], v[120:121], off offset:1152
	global_load_dwordx4 v[72:75], v[122:123], off offset:1152
	global_load_dwordx4 v[76:79], v[124:125], off offset:1152
	global_load_dwordx4 v[60:63], v[126:127], off offset:1152
	s_waitcnt lgkmcnt(0)
	s_barrier
	ds_read_b128 v[16:19], v137
	ds_read_b128 v[52:55], v137 offset:2560
	ds_read_b128 v[64:67], v137 offset:5120
	ds_read_b128 v[80:83], v137 offset:7680
	ds_read_b128 v[84:87], v138
	ds_read_b128 v[200:203], v138 offset:2560
	ds_read_b128 v[204:207], v138 offset:5120
	ds_read_b128 v[212:215], v138 offset:7680
	s_waitcnt lgkmcnt(3)
	v_mfma_f32_16x16x32_bf16 v[148:151], v[16:19], v[84:87], v[148:151]
	s_waitcnt lgkmcnt(2)
	v_mfma_f32_16x16x32_bf16 v[152:155], v[16:19], v[200:203], v[152:155]
	s_waitcnt lgkmcnt(1)
	v_mfma_f32_16x16x32_bf16 v[156:159], v[16:19], v[204:207], v[156:159]
	s_waitcnt lgkmcnt(0)
	v_mfma_f32_16x16x32_bf16 v[16:19], v[16:19], v[212:215], v[180:183]
	ds_read_b128 v[180:183], v137 offset:64
	v_mfma_f32_16x16x32_bf16 v[172:175], v[52:55], v[84:87], v[172:175]
	v_mfma_f32_16x16x32_bf16 v[144:147], v[52:55], v[200:203], v[144:147]
	v_mfma_f32_16x16x32_bf16 v[160:163], v[52:55], v[204:207], v[160:163]
	v_mfma_f32_16x16x32_bf16 v[40:43], v[52:55], v[212:215], v[40:43]
	v_mfma_f32_16x16x32_bf16 v[52:55], v[64:67], v[84:87], v[176:179]
	v_mfma_f32_16x16x32_bf16 v[164:167], v[64:67], v[200:203], v[164:167]
	v_mfma_f32_16x16x32_bf16 v[168:171], v[64:67], v[204:207], v[168:171]
	v_mfma_f32_16x16x32_bf16 v[64:67], v[64:67], v[212:215], v[184:187]
	ds_read_b128 v[184:187], v137 offset:2624
	v_mfma_f32_16x16x32_bf16 v[84:87], v[80:83], v[84:87], v[188:191]
	ds_read_b128 v[188:191], v137 offset:5184
	v_mfma_f32_16x16x32_bf16 v[176:179], v[80:83], v[200:203], v[196:199]
	ds_read_b128 v[196:199], v138 offset:64
	ds_read_b128 v[200:203], v138 offset:2624
	v_mfma_f32_16x16x32_bf16 v[140:143], v[80:83], v[204:207], v[140:143]
	ds_read_b128 v[204:207], v138 offset:5184
	v_mfma_f32_16x16x32_bf16 v[80:83], v[80:83], v[212:215], v[192:195]
	ds_read_b128 v[192:195], v137 offset:7744
	ds_read_b128 v[212:215], v138 offset:7744
	s_waitcnt vmcnt(23)
	ds_write_b128 v136, v[0:3] offset:40960
	s_waitcnt vmcnt(22)
	ds_write_b128 v136, v[12:15] offset:46080
	s_waitcnt vmcnt(21)
	ds_write_b128 v136, v[20:23] offset:51200
	s_waitcnt vmcnt(20)
	ds_write_b128 v136, v[28:31] offset:56320
	s_waitcnt vmcnt(19)
	ds_write_b128 v136, v[56:59] offset:61440
	s_waitcnt vmcnt(18)
	ds_write_b128 v139, v[88:91] offset:5120
	s_waitcnt vmcnt(17)
	ds_write_b128 v139, v[92:95] offset:10240
	s_waitcnt vmcnt(16)
	ds_write_b128 v139, v[68:71] offset:15360
	s_waitcnt lgkmcnt(8)
	v_mfma_f32_16x16x32_bf16 v[148:151], v[180:183], v[196:199], v[148:151]
	s_waitcnt lgkmcnt(10)
	v_mfma_f32_16x16x32_bf16 v[152:155], v[180:183], v[200:203], v[152:155]
	s_waitcnt lgkmcnt(9)
	v_mfma_f32_16x16x32_bf16 v[156:159], v[180:183], v[204:207], v[156:159]
	s_waitcnt lgkmcnt(8)
	v_mfma_f32_16x16x32_bf16 v[180:183], v[180:183], v[212:215], v[16:19]
	v_mfma_f32_16x16x32_bf16 v[172:175], v[184:187], v[196:199], v[172:175]
	v_mfma_f32_16x16x32_bf16 v[144:147], v[184:187], v[200:203], v[144:147]
	v_mfma_f32_16x16x32_bf16 v[160:163], v[184:187], v[204:207], v[160:163]
	v_mfma_f32_16x16x32_bf16 v[184:187], v[184:187], v[212:215], v[40:43]
	v_mfma_f32_16x16x32_bf16 v[224:227], v[188:191], v[196:199], v[52:55]
	v_mfma_f32_16x16x32_bf16 v[164:167], v[188:191], v[200:203], v[164:167]
	v_mfma_f32_16x16x32_bf16 v[168:171], v[188:191], v[204:207], v[168:171]
	v_mfma_f32_16x16x32_bf16 v[188:191], v[188:191], v[212:215], v[64:67]
	v_mfma_f32_16x16x32_bf16 v[196:199], v[192:195], v[196:199], v[84:87]
	v_mfma_f32_16x16x32_bf16 v[176:179], v[192:195], v[200:203], v[176:179]
	v_mfma_f32_16x16x32_bf16 v[140:143], v[192:195], v[204:207], v[140:143]
	v_mfma_f32_16x16x32_bf16 v[192:195], v[192:195], v[212:215], v[80:83]
	global_load_dwordx4 v[12:15], v[134:135], off offset:1280
	global_load_dwordx4 v[16:19], v[128:129], off offset:1280
	global_load_dwordx4 v[28:31], v[130:131], off offset:1280
	global_load_dwordx4 v[40:43], v[132:133], off offset:1280
	global_load_dwordx4 v[52:55], v[120:121], off offset:1280
	global_load_dwordx4 v[80:83], v[122:123], off offset:1280
	global_load_dwordx4 v[84:87], v[124:125], off offset:1280
	global_load_dwordx4 v[64:67], v[126:127], off offset:1280
	s_waitcnt lgkmcnt(0)
	s_barrier
	ds_read_b128 v[0:3], v137 offset:40960
	ds_read_b128 v[20:23], v137 offset:43520
	ds_read_b128 v[56:59], v137 offset:46080
	ds_read_b128 v[68:71], v137 offset:48640
	ds_read_b128 v[88:91], v138 offset:40960
	ds_read_b128 v[92:95], v138 offset:43520
	ds_read_b128 v[200:203], v138 offset:46080
	ds_read_b128 v[204:207], v138 offset:48640
	s_waitcnt lgkmcnt(3)
	v_mfma_f32_16x16x32_bf16 v[148:151], v[0:3], v[88:91], v[148:151]
	s_waitcnt lgkmcnt(2)
	v_mfma_f32_16x16x32_bf16 v[152:155], v[0:3], v[92:95], v[152:155]
	s_waitcnt lgkmcnt(1)
	v_mfma_f32_16x16x32_bf16 v[156:159], v[0:3], v[200:203], v[156:159]
	s_waitcnt lgkmcnt(0)
	v_mfma_f32_16x16x32_bf16 v[0:3], v[0:3], v[204:207], v[180:183]
	ds_read_b128 v[212:215], v138 offset:48704
	v_mfma_f32_16x16x32_bf16 v[172:175], v[20:23], v[88:91], v[172:175]
	v_mfma_f32_16x16x32_bf16 v[144:147], v[20:23], v[92:95], v[144:147]
	v_mfma_f32_16x16x32_bf16 v[160:163], v[20:23], v[200:203], v[160:163]
	v_mfma_f32_16x16x32_bf16 v[20:23], v[20:23], v[204:207], v[184:187]
	ds_read_b128 v[184:187], v137 offset:43584
	v_mfma_f32_16x16x32_bf16 v[180:183], v[56:59], v[88:91], v[224:227]
	v_mfma_f32_16x16x32_bf16 v[164:167], v[56:59], v[92:95], v[164:167]
	v_mfma_f32_16x16x32_bf16 v[168:171], v[56:59], v[200:203], v[168:171]
	v_mfma_f32_16x16x32_bf16 v[56:59], v[56:59], v[204:207], v[188:191]
	ds_read_b128 v[188:191], v137 offset:46144
	v_mfma_f32_16x16x32_bf16 v[88:91], v[68:71], v[88:91], v[196:199]
	ds_read_b128 v[196:199], v138 offset:41024
	v_mfma_f32_16x16x32_bf16 v[92:95], v[68:71], v[92:95], v[176:179]
	ds_read_b128 v[176:179], v137 offset:41024
	v_mfma_f32_16x16x32_bf16 v[140:143], v[68:71], v[200:203], v[140:143]
	ds_read_b128 v[200:203], v138 offset:43584
	v_mfma_f32_16x16x32_bf16 v[68:71], v[68:71], v[204:207], v[192:195]
	ds_read_b128 v[192:195], v137 offset:48704
	ds_read_b128 v[204:207], v138 offset:46144
	s_nop 0
	s_waitcnt vmcnt(23)
	ds_write_b128 v136, v[32:35]
	s_waitcnt vmcnt(22)
	ds_write_b128 v136, v[44:47] offset:5120
	s_waitcnt vmcnt(21)
	ds_write_b128 v136, v[96:99] offset:10240
	s_waitcnt vmcnt(20)
	ds_write_b128 v136, v[100:103] offset:15360
	s_waitcnt vmcnt(19)
	ds_write_b128 v136, v[104:107] offset:20480
	s_waitcnt vmcnt(18)
	ds_write_b128 v136, v[108:111] offset:25600
	s_waitcnt vmcnt(17)
	ds_write_b128 v136, v[112:115] offset:30720
	s_waitcnt vmcnt(16)
	ds_write_b128 v136, v[116:119] offset:35840
	s_waitcnt lgkmcnt(8)
	v_mfma_f32_16x16x32_bf16 v[148:151], v[176:179], v[196:199], v[148:151]
	s_waitcnt lgkmcnt(10)
	v_mfma_f32_16x16x32_bf16 v[152:155], v[176:179], v[200:203], v[152:155]
	s_waitcnt lgkmcnt(9)
	v_mfma_f32_16x16x32_bf16 v[156:159], v[176:179], v[204:207], v[156:159]
	s_waitcnt lgkmcnt(8)
	v_mfma_f32_16x16x32_bf16 v[176:179], v[176:179], v[212:215], v[0:3]
	v_mfma_f32_16x16x32_bf16 v[172:175], v[184:187], v[196:199], v[172:175]
	v_mfma_f32_16x16x32_bf16 v[144:147], v[184:187], v[200:203], v[144:147]
	v_mfma_f32_16x16x32_bf16 v[160:163], v[184:187], v[204:207], v[160:163]
	v_mfma_f32_16x16x32_bf16 v[184:187], v[184:187], v[212:215], v[20:23]
	v_mfma_f32_16x16x32_bf16 v[180:183], v[188:191], v[196:199], v[180:183]
	v_mfma_f32_16x16x32_bf16 v[164:167], v[188:191], v[200:203], v[164:167]
	v_mfma_f32_16x16x32_bf16 v[168:171], v[188:191], v[204:207], v[168:171]
	v_mfma_f32_16x16x32_bf16 v[188:191], v[188:191], v[212:215], v[56:59]
	v_mfma_f32_16x16x32_bf16 v[196:199], v[192:195], v[196:199], v[88:91]
	v_mfma_f32_16x16x32_bf16 v[200:203], v[192:195], v[200:203], v[92:95]
	v_mfma_f32_16x16x32_bf16 v[140:143], v[192:195], v[204:207], v[140:143]
	v_mfma_f32_16x16x32_bf16 v[192:195], v[192:195], v[212:215], v[68:71]
	global_load_dwordx4 v[0:3], v[134:135], off offset:1408
	global_load_dwordx4 v[20:23], v[128:129], off offset:1408
	global_load_dwordx4 v[32:35], v[130:131], off offset:1408
	global_load_dwordx4 v[44:47], v[132:133], off offset:1408
	global_load_dwordx4 v[56:59], v[120:121], off offset:1408
	global_load_dwordx4 v[88:91], v[122:123], off offset:1408
	global_load_dwordx4 v[92:95], v[124:125], off offset:1408
	global_load_dwordx4 v[68:71], v[126:127], off offset:1408
	s_waitcnt lgkmcnt(0)
	s_barrier
	ds_read_b128 v[96:99], v137
	ds_read_b128 v[100:103], v137 offset:2560
	ds_read_b128 v[104:107], v137 offset:5120
	ds_read_b128 v[108:111], v137 offset:7680
	ds_read_b128 v[112:115], v138
	ds_read_b128 v[116:119], v138 offset:2560
	ds_read_b128 v[204:207], v138 offset:5120
	ds_read_b128 v[212:215], v138 offset:7680
	s_waitcnt lgkmcnt(3)
	v_mfma_f32_16x16x32_bf16 v[148:151], v[96:99], v[112:115], v[148:151]
	s_waitcnt lgkmcnt(2)
	v_mfma_f32_16x16x32_bf16 v[152:155], v[96:99], v[116:119], v[152:155]
	s_waitcnt lgkmcnt(1)
	v_mfma_f32_16x16x32_bf16 v[156:159], v[96:99], v[204:207], v[156:159]
	s_waitcnt lgkmcnt(0)
	v_mfma_f32_16x16x32_bf16 v[96:99], v[96:99], v[212:215], v[176:179]
	v_mfma_f32_16x16x32_bf16 v[172:175], v[100:103], v[112:115], v[172:175]
	v_mfma_f32_16x16x32_bf16 v[144:147], v[100:103], v[116:119], v[144:147]
	v_mfma_f32_16x16x32_bf16 v[160:163], v[100:103], v[204:207], v[160:163]
	v_mfma_f32_16x16x32_bf16 v[100:103], v[100:103], v[212:215], v[184:187]
	ds_read_b128 v[184:187], v137 offset:2624
	v_mfma_f32_16x16x32_bf16 v[176:179], v[104:107], v[112:115], v[180:183]
	ds_read_b128 v[180:183], v137 offset:64
	v_mfma_f32_16x16x32_bf16 v[164:167], v[104:107], v[116:119], v[164:167]
	v_mfma_f32_16x16x32_bf16 v[168:171], v[104:107], v[204:207], v[168:171]
	v_mfma_f32_16x16x32_bf16 v[104:107], v[104:107], v[212:215], v[188:191]
	ds_read_b128 v[188:191], v137 offset:5184
	v_mfma_f32_16x16x32_bf16 v[112:115], v[108:111], v[112:115], v[196:199]
	ds_read_b128 v[196:199], v138 offset:64
	v_mfma_f32_16x16x32_bf16 v[116:119], v[108:111], v[116:119], v[200:203]
	ds_read_b128 v[200:203], v138 offset:2624
	v_mfma_f32_16x16x32_bf16 v[140:143], v[108:111], v[204:207], v[140:143]
	ds_read_b128 v[204:207], v138 offset:5184
	v_mfma_f32_16x16x32_bf16 v[108:111], v[108:111], v[212:215], v[192:195]
	ds_read_b128 v[192:195], v137 offset:7744
	ds_read_b128 v[212:215], v138 offset:7744
	s_waitcnt vmcnt(23)
	ds_write_b128 v136, v[4:7] offset:40960
	s_waitcnt vmcnt(22)
	ds_write_b128 v136, v[8:11] offset:46080
	s_waitcnt vmcnt(21)
	ds_write_b128 v136, v[24:27] offset:51200
	s_waitcnt vmcnt(20)
	ds_write_b128 v136, v[36:39] offset:56320
	s_waitcnt vmcnt(19)
	ds_write_b128 v136, v[48:51] offset:61440
	s_waitcnt vmcnt(18)
	ds_write_b128 v139, v[72:75] offset:5120
	s_waitcnt vmcnt(17)
	ds_write_b128 v139, v[76:79] offset:10240
	s_waitcnt vmcnt(16)
	ds_write_b128 v139, v[60:63] offset:15360
	s_waitcnt lgkmcnt(8)
	v_mfma_f32_16x16x32_bf16 v[148:151], v[180:183], v[196:199], v[148:151]
	s_waitcnt lgkmcnt(10)
	v_mfma_f32_16x16x32_bf16 v[152:155], v[180:183], v[200:203], v[152:155]
	s_waitcnt lgkmcnt(9)
	v_mfma_f32_16x16x32_bf16 v[156:159], v[180:183], v[204:207], v[156:159]
	s_waitcnt lgkmcnt(8)
	v_mfma_f32_16x16x32_bf16 v[180:183], v[180:183], v[212:215], v[96:99]
	v_mfma_f32_16x16x32_bf16 v[172:175], v[184:187], v[196:199], v[172:175]
	v_mfma_f32_16x16x32_bf16 v[144:147], v[184:187], v[200:203], v[144:147]
	v_mfma_f32_16x16x32_bf16 v[160:163], v[184:187], v[204:207], v[160:163]
	v_mfma_f32_16x16x32_bf16 v[184:187], v[184:187], v[212:215], v[100:103]
	v_mfma_f32_16x16x32_bf16 v[176:179], v[188:191], v[196:199], v[176:179]
	v_mfma_f32_16x16x32_bf16 v[164:167], v[188:191], v[200:203], v[164:167]
	v_mfma_f32_16x16x32_bf16 v[168:171], v[188:191], v[204:207], v[168:171]
	v_mfma_f32_16x16x32_bf16 v[188:191], v[188:191], v[212:215], v[104:107]
	v_mfma_f32_16x16x32_bf16 v[196:199], v[192:195], v[196:199], v[112:115]
	v_mfma_f32_16x16x32_bf16 v[116:119], v[192:195], v[200:203], v[116:119]
	v_mfma_f32_16x16x32_bf16 v[140:143], v[192:195], v[204:207], v[140:143]
	v_mfma_f32_16x16x32_bf16 v[192:195], v[192:195], v[212:215], v[108:111]
	global_load_dwordx4 v[60:63], v[134:135], off offset:1536
	global_load_dwordx4 v[72:75], v[128:129], off offset:1536
	global_load_dwordx4 v[76:79], v[130:131], off offset:1536
	global_load_dwordx4 v[96:99], v[132:133], off offset:1536
	global_load_dwordx4 v[100:103], v[120:121], off offset:1536
	global_load_dwordx4 v[104:107], v[122:123], off offset:1536
	global_load_dwordx4 v[108:111], v[124:125], off offset:1536
	global_load_dwordx4 v[112:115], v[126:127], off offset:1536
	s_waitcnt lgkmcnt(0)
	s_barrier
	ds_read_b128 v[4:7], v137 offset:40960
	ds_read_b128 v[8:11], v137 offset:43520
	ds_read_b128 v[24:27], v137 offset:46080
	ds_read_b128 v[36:39], v137 offset:48640
	ds_read_b128 v[48:51], v138 offset:40960
	ds_read_b128 v[200:203], v138 offset:43520
	ds_read_b128 v[204:207], v138 offset:46080
	ds_read_b128 v[212:215], v138 offset:48640
	s_waitcnt lgkmcnt(3)
	v_mfma_f32_16x16x32_bf16 v[148:151], v[4:7], v[48:51], v[148:151]
	s_waitcnt lgkmcnt(2)
	v_mfma_f32_16x16x32_bf16 v[152:155], v[4:7], v[200:203], v[152:155]
	s_waitcnt lgkmcnt(1)
	v_mfma_f32_16x16x32_bf16 v[156:159], v[4:7], v[204:207], v[156:159]
	s_waitcnt lgkmcnt(0)
	v_mfma_f32_16x16x32_bf16 v[4:7], v[4:7], v[212:215], v[180:183]
	ds_read_b128 v[180:183], v137 offset:41024
	v_mfma_f32_16x16x32_bf16 v[172:175], v[8:11], v[48:51], v[172:175]
	v_mfma_f32_16x16x32_bf16 v[144:147], v[8:11], v[200:203], v[144:147]
	v_mfma_f32_16x16x32_bf16 v[160:163], v[8:11], v[204:207], v[160:163]
	v_mfma_f32_16x16x32_bf16 v[8:11], v[8:11], v[212:215], v[184:187]
	ds_read_b128 v[184:187], v137 offset:43584
	v_mfma_f32_16x16x32_bf16 v[176:179], v[24:27], v[48:51], v[176:179]
	v_mfma_f32_16x16x32_bf16 v[164:167], v[24:27], v[200:203], v[164:167]
	v_mfma_f32_16x16x32_bf16 v[168:171], v[24:27], v[204:207], v[168:171]
	v_mfma_f32_16x16x32_bf16 v[24:27], v[24:27], v[212:215], v[188:191]
	ds_read_b128 v[188:191], v137 offset:46144
	v_mfma_f32_16x16x32_bf16 v[48:51], v[36:39], v[48:51], v[196:199]
	ds_read_b128 v[196:199], v138 offset:41024
	v_mfma_f32_16x16x32_bf16 v[116:119], v[36:39], v[200:203], v[116:119]
	ds_read_b128 v[200:203], v138 offset:43584
	v_mfma_f32_16x16x32_bf16 v[140:143], v[36:39], v[204:207], v[140:143]
	ds_read_b128 v[204:207], v138 offset:46144
	v_mfma_f32_16x16x32_bf16 v[36:39], v[36:39], v[212:215], v[192:195]
	ds_read_b128 v[192:195], v137 offset:48704
	ds_read_b128 v[212:215], v138 offset:48704
	s_waitcnt vmcnt(23)
	ds_write_b128 v136, v[12:15]
	s_waitcnt vmcnt(22)
	ds_write_b128 v136, v[16:19] offset:5120
	s_waitcnt vmcnt(21)
	ds_write_b128 v136, v[28:31] offset:10240
	s_waitcnt vmcnt(20)
	ds_write_b128 v136, v[40:43] offset:15360
	s_waitcnt vmcnt(19)
	ds_write_b128 v136, v[52:55] offset:20480
	s_waitcnt vmcnt(18)
	ds_write_b128 v136, v[80:83] offset:25600
	s_waitcnt vmcnt(17)
	ds_write_b128 v136, v[84:87] offset:30720
	s_waitcnt vmcnt(16)
	ds_write_b128 v136, v[64:67] offset:35840
	s_waitcnt lgkmcnt(8)
	v_mfma_f32_16x16x32_bf16 v[148:151], v[180:183], v[196:199], v[148:151]
	s_waitcnt lgkmcnt(10)
	v_mfma_f32_16x16x32_bf16 v[152:155], v[180:183], v[200:203], v[152:155]
	s_waitcnt lgkmcnt(9)
	v_mfma_f32_16x16x32_bf16 v[156:159], v[180:183], v[204:207], v[156:159]
	s_waitcnt lgkmcnt(8)
	v_mfma_f32_16x16x32_bf16 v[180:183], v[180:183], v[212:215], v[4:7]
	v_mfma_f32_16x16x32_bf16 v[172:175], v[184:187], v[196:199], v[172:175]
	v_mfma_f32_16x16x32_bf16 v[144:147], v[184:187], v[200:203], v[144:147]
	v_mfma_f32_16x16x32_bf16 v[160:163], v[184:187], v[204:207], v[160:163]
	v_mfma_f32_16x16x32_bf16 v[184:187], v[184:187], v[212:215], v[8:11]
	v_mfma_f32_16x16x32_bf16 v[176:179], v[188:191], v[196:199], v[176:179]
	v_mfma_f32_16x16x32_bf16 v[164:167], v[188:191], v[200:203], v[164:167]
	v_mfma_f32_16x16x32_bf16 v[168:171], v[188:191], v[204:207], v[168:171]
	v_mfma_f32_16x16x32_bf16 v[188:191], v[188:191], v[212:215], v[24:27]
	v_mfma_f32_16x16x32_bf16 v[48:51], v[192:195], v[196:199], v[48:51]
	v_mfma_f32_16x16x32_bf16 v[116:119], v[192:195], v[200:203], v[116:119]
	v_mfma_f32_16x16x32_bf16 v[140:143], v[192:195], v[204:207], v[140:143]
	v_mfma_f32_16x16x32_bf16 v[192:195], v[192:195], v[212:215], v[36:39]
	global_load_dwordx4 v[4:7], v[134:135], off offset:1664
	global_load_dwordx4 v[12:15], v[128:129], off offset:1664
	global_load_dwordx4 v[8:11], v[130:131], off offset:1664
	global_load_dwordx4 v[16:19], v[132:133], off offset:1664
	global_load_dwordx4 v[24:27], v[120:121], off offset:1664
	global_load_dwordx4 v[28:31], v[122:123], off offset:1664
	global_load_dwordx4 v[36:39], v[124:125], off offset:1664
	global_load_dwordx4 v[40:43], v[126:127], off offset:1664
	s_waitcnt lgkmcnt(0)
	s_barrier
	ds_read_b128 v[52:55], v137
	ds_read_b128 v[64:67], v137 offset:2560
	ds_read_b128 v[80:83], v137 offset:5120
	ds_read_b128 v[84:87], v137 offset:7680
	ds_read_b128 v[196:199], v138
	ds_read_b128 v[200:203], v138 offset:2560
	ds_read_b128 v[204:207], v138 offset:5120
	ds_read_b128 v[212:215], v138 offset:7680
	s_waitcnt lgkmcnt(3)
	v_mfma_f32_16x16x32_bf16 v[148:151], v[52:55], v[196:199], v[148:151]
	s_waitcnt lgkmcnt(2)
	v_mfma_f32_16x16x32_bf16 v[152:155], v[52:55], v[200:203], v[152:155]
	s_waitcnt lgkmcnt(1)
	v_mfma_f32_16x16x32_bf16 v[156:159], v[52:55], v[204:207], v[156:159]
	s_waitcnt lgkmcnt(0)
	v_mfma_f32_16x16x32_bf16 v[52:55], v[52:55], v[212:215], v[180:183]
	ds_read_b128 v[180:183], v137 offset:64
	v_mfma_f32_16x16x32_bf16 v[172:175], v[64:67], v[196:199], v[172:175]
	v_mfma_f32_16x16x32_bf16 v[144:147], v[64:67], v[200:203], v[144:147]
	v_mfma_f32_16x16x32_bf16 v[160:163], v[64:67], v[204:207], v[160:163]
	v_mfma_f32_16x16x32_bf16 v[64:67], v[64:67], v[212:215], v[184:187]
	ds_read_b128 v[184:187], v137 offset:2624
	v_mfma_f32_16x16x32_bf16 v[176:179], v[80:83], v[196:199], v[176:179]
	v_mfma_f32_16x16x32_bf16 v[164:167], v[80:83], v[200:203], v[164:167]
	v_mfma_f32_16x16x32_bf16 v[168:171], v[80:83], v[204:207], v[168:171]
	v_mfma_f32_16x16x32_bf16 v[80:83], v[80:83], v[212:215], v[188:191]
	ds_read_b128 v[188:191], v137 offset:5184
	v_mfma_f32_16x16x32_bf16 v[48:51], v[84:87], v[196:199], v[48:51]
	ds_read_b128 v[196:199], v138 offset:64
	v_mfma_f32_16x16x32_bf16 v[116:119], v[84:87], v[200:203], v[116:119]
	ds_read_b128 v[200:203], v138 offset:2624
	v_mfma_f32_16x16x32_bf16 v[140:143], v[84:87], v[204:207], v[140:143]
	ds_read_b128 v[204:207], v138 offset:5184
	v_mfma_f32_16x16x32_bf16 v[84:87], v[84:87], v[212:215], v[192:195]
	ds_read_b128 v[192:195], v137 offset:7744
	ds_read_b128 v[212:215], v138 offset:7744
	s_waitcnt vmcnt(23)
	ds_write_b128 v136, v[0:3] offset:40960
	s_waitcnt vmcnt(22)
	ds_write_b128 v136, v[20:23] offset:46080
	s_waitcnt vmcnt(21)
	ds_write_b128 v136, v[32:35] offset:51200
	s_waitcnt vmcnt(20)
	ds_write_b128 v136, v[44:47] offset:56320
	s_waitcnt vmcnt(19)
	ds_write_b128 v136, v[56:59] offset:61440
	s_waitcnt vmcnt(18)
	ds_write_b128 v139, v[88:91] offset:5120
	s_waitcnt vmcnt(17)
	ds_write_b128 v139, v[92:95] offset:10240
	s_waitcnt vmcnt(16)
	ds_write_b128 v139, v[68:71] offset:15360
	s_waitcnt lgkmcnt(8)
	v_mfma_f32_16x16x32_bf16 v[148:151], v[180:183], v[196:199], v[148:151]
	s_waitcnt lgkmcnt(10)
	v_mfma_f32_16x16x32_bf16 v[152:155], v[180:183], v[200:203], v[152:155]
	s_waitcnt lgkmcnt(9)
	v_mfma_f32_16x16x32_bf16 v[156:159], v[180:183], v[204:207], v[156:159]
	s_waitcnt lgkmcnt(8)
	v_mfma_f32_16x16x32_bf16 v[180:183], v[180:183], v[212:215], v[52:55]
	v_mfma_f32_16x16x32_bf16 v[172:175], v[184:187], v[196:199], v[172:175]
	v_mfma_f32_16x16x32_bf16 v[144:147], v[184:187], v[200:203], v[144:147]
	v_mfma_f32_16x16x32_bf16 v[160:163], v[184:187], v[204:207], v[160:163]
	v_mfma_f32_16x16x32_bf16 v[184:187], v[184:187], v[212:215], v[64:67]
	v_mfma_f32_16x16x32_bf16 v[176:179], v[188:191], v[196:199], v[176:179]
	v_mfma_f32_16x16x32_bf16 v[164:167], v[188:191], v[200:203], v[164:167]
	v_mfma_f32_16x16x32_bf16 v[168:171], v[188:191], v[204:207], v[168:171]
	v_mfma_f32_16x16x32_bf16 v[80:83], v[188:191], v[212:215], v[80:83]
	v_mfma_f32_16x16x32_bf16 v[188:191], v[192:195], v[196:199], v[48:51]
	global_load_dwordx4 v[20:23], v[134:135], off offset:1792
	s_nop 1
	global_load_dwordx4 v[48:51], v[128:129], off offset:1792
	global_load_dwordx4 v[32:35], v[130:131], off offset:1792
	global_load_dwordx4 v[44:47], v[132:133], off offset:1792
	global_load_dwordx4 v[52:55], v[120:121], off offset:1792
	global_load_dwordx4 v[56:59], v[122:123], off offset:1792
	global_load_dwordx4 v[64:67], v[124:125], off offset:1792
	global_load_dwordx4 v[68:71], v[126:127], off offset:1792
	s_waitcnt lgkmcnt(0)
	s_barrier
	v_mfma_f32_16x16x32_bf16 v[116:119], v[192:195], v[200:203], v[116:119]
	v_mfma_f32_16x16x32_bf16 v[140:143], v[192:195], v[204:207], v[140:143]
	v_mfma_f32_16x16x32_bf16 v[84:87], v[192:195], v[212:215], v[84:87]
	ds_read_b128 v[0:3], v137 offset:40960
	ds_read_b128 v[88:91], v137 offset:43520
	ds_read_b128 v[92:95], v137 offset:46080
	ds_read_b128 v[192:195], v137 offset:48640
	ds_read_b128 v[196:199], v138 offset:40960
	ds_read_b128 v[200:203], v138 offset:43520
	ds_read_b128 v[204:207], v138 offset:46080
	ds_read_b128 v[212:215], v138 offset:48640
	s_waitcnt lgkmcnt(3)
	v_mfma_f32_16x16x32_bf16 v[148:151], v[0:3], v[196:199], v[148:151]
	s_waitcnt lgkmcnt(2)
	v_mfma_f32_16x16x32_bf16 v[152:155], v[0:3], v[200:203], v[152:155]
	s_waitcnt lgkmcnt(1)
	v_mfma_f32_16x16x32_bf16 v[156:159], v[0:3], v[204:207], v[156:159]
	s_waitcnt lgkmcnt(0)
	v_mfma_f32_16x16x32_bf16 v[0:3], v[0:3], v[212:215], v[180:183]
	ds_read_b128 v[180:183], v137 offset:41024
	v_mfma_f32_16x16x32_bf16 v[172:175], v[88:91], v[196:199], v[172:175]
	v_mfma_f32_16x16x32_bf16 v[144:147], v[88:91], v[200:203], v[144:147]
	v_mfma_f32_16x16x32_bf16 v[160:163], v[88:91], v[204:207], v[160:163]
	v_mfma_f32_16x16x32_bf16 v[88:91], v[88:91], v[212:215], v[184:187]
	ds_read_b128 v[184:187], v137 offset:43584
	v_mfma_f32_16x16x32_bf16 v[176:179], v[92:95], v[196:199], v[176:179]
	v_mfma_f32_16x16x32_bf16 v[164:167], v[92:95], v[200:203], v[164:167]
	v_mfma_f32_16x16x32_bf16 v[168:171], v[92:95], v[204:207], v[168:171]
	v_mfma_f32_16x16x32_bf16 v[80:83], v[92:95], v[212:215], v[80:83]
	v_mfma_f32_16x16x32_bf16 v[92:95], v[192:195], v[196:199], v[188:191]
	ds_read_b128 v[188:191], v137 offset:46144
	ds_read_b128 v[196:199], v138 offset:41024
	v_mfma_f32_16x16x32_bf16 v[116:119], v[192:195], v[200:203], v[116:119]
	ds_read_b128 v[200:203], v138 offset:43584
	v_mfma_f32_16x16x32_bf16 v[140:143], v[192:195], v[204:207], v[140:143]
	ds_read_b128 v[204:207], v138 offset:46144
	v_mfma_f32_16x16x32_bf16 v[84:87], v[192:195], v[212:215], v[84:87]
	ds_read_b128 v[192:195], v137 offset:48704
	ds_read_b128 v[212:215], v138 offset:48704
	s_waitcnt vmcnt(23)
	ds_write_b128 v136, v[60:63]
	s_waitcnt vmcnt(22)
	ds_write_b128 v136, v[72:75] offset:5120
	s_waitcnt vmcnt(21)
	ds_write_b128 v136, v[76:79] offset:10240
	s_waitcnt vmcnt(20)
	ds_write_b128 v136, v[96:99] offset:15360
	s_waitcnt vmcnt(19)
	ds_write_b128 v136, v[100:103] offset:20480
	s_waitcnt vmcnt(18)
	ds_write_b128 v136, v[104:107] offset:25600
	s_waitcnt vmcnt(17)
	ds_write_b128 v136, v[108:111] offset:30720
	s_waitcnt vmcnt(16)
	ds_write_b128 v136, v[112:115] offset:35840
	s_waitcnt lgkmcnt(8)
	v_mfma_f32_16x16x32_bf16 v[148:151], v[180:183], v[196:199], v[148:151]
	s_waitcnt lgkmcnt(10)
	v_mfma_f32_16x16x32_bf16 v[152:155], v[180:183], v[200:203], v[152:155]
	s_waitcnt lgkmcnt(9)
	v_mfma_f32_16x16x32_bf16 v[156:159], v[180:183], v[204:207], v[156:159]
	s_waitcnt lgkmcnt(8)
	v_mfma_f32_16x16x32_bf16 v[180:183], v[180:183], v[212:215], v[0:3]
	v_mfma_f32_16x16x32_bf16 v[172:175], v[184:187], v[196:199], v[172:175]
	v_mfma_f32_16x16x32_bf16 v[144:147], v[184:187], v[200:203], v[144:147]
	v_mfma_f32_16x16x32_bf16 v[160:163], v[184:187], v[204:207], v[160:163]
	v_mfma_f32_16x16x32_bf16 v[184:187], v[184:187], v[212:215], v[88:91]
	v_mfma_f32_16x16x32_bf16 v[176:179], v[188:191], v[196:199], v[176:179]
	v_mfma_f32_16x16x32_bf16 v[164:167], v[188:191], v[200:203], v[164:167]
	v_mfma_f32_16x16x32_bf16 v[168:171], v[188:191], v[204:207], v[168:171]
	v_mfma_f32_16x16x32_bf16 v[188:191], v[188:191], v[212:215], v[80:83]
	v_mfma_f32_16x16x32_bf16 v[196:199], v[192:195], v[196:199], v[92:95]
	v_mfma_f32_16x16x32_bf16 v[116:119], v[192:195], v[200:203], v[116:119]
	v_mfma_f32_16x16x32_bf16 v[140:143], v[192:195], v[204:207], v[140:143]
	v_mfma_f32_16x16x32_bf16 v[192:195], v[192:195], v[212:215], v[84:87]
	global_load_dwordx4 v[0:3], v[134:135], off offset:1920
	global_load_dwordx4 v[76:79], v[128:129], off offset:1920
	global_load_dwordx4 v[60:63], v[130:131], off offset:1920
	global_load_dwordx4 v[72:75], v[132:133], off offset:1920
	global_load_dwordx4 v[80:83], v[120:121], off offset:1920
	global_load_dwordx4 v[84:87], v[122:123], off offset:1920
	global_load_dwordx4 v[88:91], v[124:125], off offset:1920
	global_load_dwordx4 v[92:95], v[126:127], off offset:1920
	s_waitcnt lgkmcnt(0)
	s_barrier
	ds_read_b128 v[96:99], v137
	ds_read_b128 v[100:103], v137 offset:2560
	ds_read_b128 v[104:107], v137 offset:5120
	ds_read_b128 v[108:111], v137 offset:7680
	ds_read_b128 v[112:115], v138
	ds_read_b128 v[120:123], v138 offset:2560
	ds_read_b128 v[124:127], v138 offset:5120
	ds_read_b128 v[128:131], v138 offset:7680
	s_waitcnt lgkmcnt(3)
	v_mfma_f32_16x16x32_bf16 v[132:135], v[96:99], v[112:115], v[148:151]
	s_waitcnt lgkmcnt(2)
	v_mfma_f32_16x16x32_bf16 v[148:151], v[96:99], v[120:123], v[152:155]
	s_waitcnt lgkmcnt(1)
	v_mfma_f32_16x16x32_bf16 v[152:155], v[96:99], v[124:127], v[156:159]
	s_waitcnt lgkmcnt(0)
	v_mfma_f32_16x16x32_bf16 v[96:99], v[96:99], v[128:131], v[180:183]
	ds_read_b128 v[180:183], v138 offset:64
	v_mfma_f32_16x16x32_bf16 v[156:159], v[100:103], v[112:115], v[172:175]
	v_mfma_f32_16x16x32_bf16 v[144:147], v[100:103], v[120:123], v[144:147]
	v_mfma_f32_16x16x32_bf16 v[160:163], v[100:103], v[124:127], v[160:163]
	v_mfma_f32_16x16x32_bf16 v[100:103], v[100:103], v[128:131], v[184:187]
	ds_read_b128 v[184:187], v138 offset:2624
	v_mfma_f32_16x16x32_bf16 v[172:175], v[104:107], v[112:115], v[176:179]
	ds_read_b128 v[176:179], v137 offset:7744
	v_mfma_f32_16x16x32_bf16 v[164:167], v[104:107], v[120:123], v[164:167]
	v_mfma_f32_16x16x32_bf16 v[168:171], v[104:107], v[124:127], v[168:171]
	v_mfma_f32_16x16x32_bf16 v[104:107], v[104:107], v[128:131], v[188:191]
	ds_read_b128 v[188:191], v138 offset:5184
	v_mfma_f32_16x16x32_bf16 v[112:115], v[108:111], v[112:115], v[196:199]
	v_mfma_f32_16x16x32_bf16 v[116:119], v[108:111], v[120:123], v[116:119]
	v_mfma_f32_16x16x32_bf16 v[120:123], v[108:111], v[124:127], v[140:143]
	ds_read_b128 v[124:127], v137 offset:64
	ds_read_b128 v[140:143], v137 offset:5184
	v_mfma_f32_16x16x32_bf16 v[108:111], v[108:111], v[128:131], v[192:195]
	ds_read_b128 v[128:131], v137 offset:2624
	ds_read_b128 v[192:195], v138 offset:7744
	s_waitcnt vmcnt(23)
	ds_write_b128 v136, v[4:7] offset:40960
	s_waitcnt vmcnt(22)
	ds_write_b128 v136, v[12:15] offset:46080
	s_waitcnt vmcnt(21)
	ds_write_b128 v136, v[8:11] offset:51200
	s_waitcnt vmcnt(20)
	ds_write_b128 v136, v[16:19] offset:56320
	s_waitcnt vmcnt(19)
	ds_write_b128 v136, v[24:27] offset:61440
	s_waitcnt vmcnt(18)
	ds_write_b128 v139, v[28:31] offset:5120
	s_waitcnt vmcnt(17)
	ds_write_b128 v139, v[36:39] offset:10240
	s_waitcnt vmcnt(16)
	ds_write_b128 v139, v[40:43] offset:15360
	s_waitcnt lgkmcnt(8)
	s_barrier
	ds_read_b128 v[4:7], v137 offset:40960
	ds_read_b128 v[8:11], v137 offset:43520
	ds_read_b128 v[12:15], v137 offset:46080
	ds_read_b128 v[16:19], v137 offset:48640
	ds_read_b128 v[24:27], v138 offset:40960
	ds_read_b128 v[28:31], v138 offset:43520
	ds_read_b128 v[36:39], v138 offset:46080
	ds_read_b128 v[40:43], v138 offset:48640
	v_mfma_f32_16x16x32_bf16 v[132:135], v[124:127], v[180:183], v[132:135]
	v_mfma_f32_16x16x32_bf16 v[148:151], v[124:127], v[184:187], v[148:151]
	v_mfma_f32_16x16x32_bf16 v[152:155], v[124:127], v[188:191], v[152:155]
	v_mfma_f32_16x16x32_bf16 v[96:99], v[124:127], v[192:195], v[96:99]
	v_mfma_f32_16x16x32_bf16 v[124:127], v[128:131], v[180:183], v[156:159]
	v_mfma_f32_16x16x32_bf16 v[144:147], v[128:131], v[184:187], v[144:147]
	v_mfma_f32_16x16x32_bf16 v[156:159], v[128:131], v[188:191], v[160:163]
	v_mfma_f32_16x16x32_bf16 v[100:103], v[128:131], v[192:195], v[100:103]
	v_mfma_f32_16x16x32_bf16 v[128:131], v[140:143], v[180:183], v[172:175]
	v_mfma_f32_16x16x32_bf16 v[160:163], v[140:143], v[184:187], v[164:167]
	v_mfma_f32_16x16x32_bf16 v[164:167], v[140:143], v[188:191], v[168:171]
	v_mfma_f32_16x16x32_bf16 v[104:107], v[140:143], v[192:195], v[104:107]
	v_mfma_f32_16x16x32_bf16 v[112:115], v[176:179], v[180:183], v[112:115]
	v_mfma_f32_16x16x32_bf16 v[116:119], v[176:179], v[184:187], v[116:119]
	v_mfma_f32_16x16x32_bf16 v[120:123], v[176:179], v[188:191], v[120:123]
	v_mfma_f32_16x16x32_bf16 v[108:111], v[176:179], v[192:195], v[108:111]
	s_waitcnt lgkmcnt(3)
	v_mfma_f32_16x16x32_bf16 v[132:135], v[4:7], v[24:27], v[132:135]
	s_waitcnt lgkmcnt(2)
	v_mfma_f32_16x16x32_bf16 v[140:143], v[4:7], v[28:31], v[148:151]
	s_waitcnt lgkmcnt(1)
	v_mfma_f32_16x16x32_bf16 v[148:151], v[4:7], v[36:39], v[152:155]
	s_waitcnt lgkmcnt(0)
	v_mfma_f32_16x16x32_bf16 v[4:7], v[4:7], v[40:43], v[96:99]
	v_mfma_f32_16x16x32_bf16 v[96:99], v[8:11], v[24:27], v[124:127]
	v_mfma_f32_16x16x32_bf16 v[124:127], v[8:11], v[28:31], v[144:147]
	v_mfma_f32_16x16x32_bf16 v[144:147], v[8:11], v[36:39], v[156:159]
	ds_read_b128 v[156:159], v138 offset:46144
	v_mfma_f32_16x16x32_bf16 v[8:11], v[8:11], v[40:43], v[100:103]
	v_mfma_f32_16x16x32_bf16 v[100:103], v[12:15], v[24:27], v[128:131]
	v_mfma_f32_16x16x32_bf16 v[128:131], v[12:15], v[28:31], v[160:163]
	ds_read_b128 v[160:163], v138 offset:48704
	v_mfma_f32_16x16x32_bf16 v[152:155], v[12:15], v[36:39], v[164:167]
	v_mfma_f32_16x16x32_bf16 v[12:15], v[12:15], v[40:43], v[104:107]
	ds_read_b128 v[104:107], v137 offset:43584
	v_mfma_f32_16x16x32_bf16 v[24:27], v[16:19], v[24:27], v[112:115]
	ds_read_b128 v[112:115], v137 offset:48704
	v_mfma_f32_16x16x32_bf16 v[28:31], v[16:19], v[28:31], v[116:119]
	ds_read_b128 v[116:119], v138 offset:41024
	v_mfma_f32_16x16x32_bf16 v[36:39], v[16:19], v[36:39], v[120:123]
	ds_read_b128 v[120:123], v138 offset:43584
	v_mfma_f32_16x16x32_bf16 v[16:19], v[16:19], v[40:43], v[108:111]
	ds_read_b128 v[40:43], v137 offset:41024
	ds_read_b128 v[108:111], v137 offset:46144
	s_nop 0
	s_waitcnt vmcnt(15)
	ds_write_b128 v136, v[20:23]
	s_waitcnt vmcnt(14)
	ds_write_b128 v136, v[48:51] offset:5120
	s_waitcnt vmcnt(13)
	ds_write_b128 v136, v[32:35] offset:10240
	s_waitcnt vmcnt(12)
	ds_write_b128 v136, v[44:47] offset:15360
	s_waitcnt vmcnt(11)
	ds_write_b128 v136, v[52:55] offset:20480
	s_waitcnt vmcnt(10)
	ds_write_b128 v136, v[56:59] offset:25600
	s_waitcnt vmcnt(9)
	ds_write_b128 v136, v[64:67] offset:30720
	s_waitcnt vmcnt(8)
	ds_write_b128 v136, v[68:71] offset:35840
	s_waitcnt lgkmcnt(8)
	s_barrier
	ds_read_b128 v[20:23], v137
	ds_read_b128 v[32:35], v137 offset:2560
	ds_read_b128 v[44:47], v137 offset:5120
	ds_read_b128 v[48:51], v137 offset:7680
	ds_read_b128 v[52:55], v138
	ds_read_b128 v[56:59], v138 offset:2560
	ds_read_b128 v[64:67], v138 offset:5120
	ds_read_b128 v[68:71], v138 offset:7680
	v_mfma_f32_16x16x32_bf16 v[132:135], v[40:43], v[116:119], v[132:135]
	v_mfma_f32_16x16x32_bf16 v[140:143], v[40:43], v[120:123], v[140:143]
	v_mfma_f32_16x16x32_bf16 v[148:151], v[40:43], v[156:159], v[148:151]
	v_mfma_f32_16x16x32_bf16 v[4:7], v[40:43], v[160:163], v[4:7]
	v_mfma_f32_16x16x32_bf16 v[40:43], v[104:107], v[116:119], v[96:99]
	v_mfma_f32_16x16x32_bf16 v[96:99], v[104:107], v[120:123], v[124:127]
	v_mfma_f32_16x16x32_bf16 v[124:127], v[104:107], v[156:159], v[144:147]
	v_mfma_f32_16x16x32_bf16 v[8:11], v[104:107], v[160:163], v[8:11]
	v_mfma_f32_16x16x32_bf16 v[100:103], v[108:111], v[116:119], v[100:103]
	v_mfma_f32_16x16x32_bf16 v[104:107], v[108:111], v[120:123], v[128:131]
	v_mfma_f32_16x16x32_bf16 v[128:131], v[108:111], v[156:159], v[152:155]
	v_mfma_f32_16x16x32_bf16 v[12:15], v[108:111], v[160:163], v[12:15]
	v_mfma_f32_16x16x32_bf16 v[24:27], v[112:115], v[116:119], v[24:27]
	v_mfma_f32_16x16x32_bf16 v[28:31], v[112:115], v[120:123], v[28:31]
	ds_read_b128 v[120:123], v138 offset:5184
	v_mfma_f32_16x16x32_bf16 v[36:39], v[112:115], v[156:159], v[36:39]
	v_mfma_f32_16x16x32_bf16 v[16:19], v[112:115], v[160:163], v[16:19]
	s_waitcnt lgkmcnt(3)
	v_mfma_f32_16x16x32_bf16 v[108:111], v[20:23], v[52:55], v[132:135]
	s_waitcnt lgkmcnt(2)
	v_mfma_f32_16x16x32_bf16 v[112:115], v[20:23], v[56:59], v[140:143]
	s_waitcnt lgkmcnt(1)
	v_mfma_f32_16x16x32_bf16 v[116:119], v[20:23], v[64:67], v[148:151]
	s_waitcnt lgkmcnt(0)
	v_mfma_f32_16x16x32_bf16 v[4:7], v[20:23], v[68:71], v[4:7]
	v_mfma_f32_16x16x32_bf16 v[20:23], v[32:35], v[52:55], v[40:43]
	v_mfma_f32_16x16x32_bf16 v[40:43], v[32:35], v[56:59], v[96:99]
	v_mfma_f32_16x16x32_bf16 v[96:99], v[32:35], v[64:67], v[124:127]
	ds_read_b128 v[124:127], v138 offset:7744
	v_mfma_f32_16x16x32_bf16 v[8:11], v[32:35], v[68:71], v[8:11]
	v_mfma_f32_16x16x32_bf16 v[32:35], v[44:47], v[52:55], v[100:103]
	v_mfma_f32_16x16x32_bf16 v[100:103], v[44:47], v[56:59], v[104:107]
	v_mfma_f32_16x16x32_bf16 v[104:107], v[44:47], v[64:67], v[128:131]
	v_mfma_f32_16x16x32_bf16 v[12:15], v[44:47], v[68:71], v[12:15]
	ds_read_b128 v[44:47], v137 offset:64
	v_mfma_f32_16x16x32_bf16 v[24:27], v[48:51], v[52:55], v[24:27]
	ds_read_b128 v[52:55], v137 offset:5184
	v_mfma_f32_16x16x32_bf16 v[28:31], v[48:51], v[56:59], v[28:31]
	ds_read_b128 v[56:59], v137 offset:7744
	v_mfma_f32_16x16x32_bf16 v[36:39], v[48:51], v[64:67], v[36:39]
	ds_read_b128 v[64:67], v138 offset:64
	v_mfma_f32_16x16x32_bf16 v[16:19], v[48:51], v[68:71], v[16:19]
	ds_read_b128 v[48:51], v137 offset:2624
	ds_read_b128 v[68:71], v138 offset:2624
	s_waitcnt vmcnt(7)
	ds_write_b128 v136, v[0:3] offset:40960
	s_waitcnt vmcnt(6)
	ds_write_b128 v136, v[76:79] offset:46080
	s_waitcnt vmcnt(5)
	ds_write_b128 v136, v[60:63] offset:51200
	s_waitcnt vmcnt(4)
	ds_write_b128 v136, v[72:75] offset:56320
	s_waitcnt vmcnt(3)
	ds_write_b128 v136, v[80:83] offset:61440
	s_waitcnt vmcnt(2)
	ds_write_b128 v139, v[84:87] offset:5120
	s_waitcnt vmcnt(1)
	ds_write_b128 v139, v[88:91] offset:10240
	s_waitcnt vmcnt(0)
	ds_write_b128 v139, v[92:95] offset:15360
	s_waitcnt lgkmcnt(8)
	v_mfma_f32_16x16x32_bf16 v[108:111], v[44:47], v[64:67], v[108:111]
	s_barrier
	v_mfma_f32_16x16x32_bf16 v[112:115], v[44:47], v[68:71], v[112:115]
	v_mfma_f32_16x16x32_bf16 v[116:119], v[44:47], v[120:123], v[116:119]
	v_mfma_f32_16x16x32_bf16 v[4:7], v[44:47], v[124:127], v[4:7]
	v_mfma_f32_16x16x32_bf16 v[20:23], v[48:51], v[64:67], v[20:23]
	v_mfma_f32_16x16x32_bf16 v[40:43], v[48:51], v[68:71], v[40:43]
	v_mfma_f32_16x16x32_bf16 v[44:47], v[48:51], v[120:123], v[96:99]
	v_mfma_f32_16x16x32_bf16 v[8:11], v[48:51], v[124:127], v[8:11]
	v_mfma_f32_16x16x32_bf16 v[32:35], v[52:55], v[64:67], v[32:35]
	v_mfma_f32_16x16x32_bf16 v[48:51], v[52:55], v[68:71], v[100:103]
	v_mfma_f32_16x16x32_bf16 v[96:99], v[52:55], v[120:123], v[104:107]
	v_mfma_f32_16x16x32_bf16 v[12:15], v[52:55], v[124:127], v[12:15]
	v_mfma_f32_16x16x32_bf16 v[24:27], v[56:59], v[64:67], v[24:27]
	v_mfma_f32_16x16x32_bf16 v[28:31], v[56:59], v[68:71], v[28:31]
	v_mfma_f32_16x16x32_bf16 v[36:39], v[56:59], v[120:123], v[36:39]
	v_mfma_f32_16x16x32_bf16 v[16:19], v[56:59], v[124:127], v[16:19]
	ds_read_b128 v[0:3], v137 offset:40960
	ds_read_b128 v[52:55], v137 offset:43520
	ds_read_b128 v[56:59], v137 offset:46080
	ds_read_b128 v[60:63], v137 offset:48640
	ds_read_b128 v[64:67], v138 offset:40960
	ds_read_b128 v[68:71], v138 offset:43520
	ds_read_b128 v[72:75], v138 offset:46080
	ds_read_b128 v[76:79], v138 offset:48640
	s_waitcnt lgkmcnt(3)
	v_mfma_f32_16x16x32_bf16 v[80:83], v[0:3], v[64:67], v[108:111]
	s_waitcnt lgkmcnt(2)
	v_mfma_f32_16x16x32_bf16 v[84:87], v[0:3], v[68:71], v[112:115]
	s_waitcnt lgkmcnt(1)
	v_mfma_f32_16x16x32_bf16 v[88:91], v[0:3], v[72:75], v[116:119]
	s_waitcnt lgkmcnt(0)
	v_mfma_f32_16x16x32_bf16 v[0:3], v[0:3], v[76:79], v[4:7]
	ds_read_b128 v[92:95], v138 offset:48704
	v_mfma_f32_16x16x32_bf16 v[4:7], v[52:55], v[64:67], v[20:23]
	v_mfma_f32_16x16x32_bf16 v[20:23], v[52:55], v[68:71], v[40:43]
	v_mfma_f32_16x16x32_bf16 v[40:43], v[52:55], v[72:75], v[44:47]
	v_mfma_f32_16x16x32_bf16 v[8:11], v[52:55], v[76:79], v[8:11]
	ds_read_b128 v[52:55], v137 offset:41024
	v_mfma_f32_16x16x32_bf16 v[32:35], v[56:59], v[64:67], v[32:35]
	v_mfma_f32_16x16x32_bf16 v[44:47], v[56:59], v[68:71], v[48:51]
	v_mfma_f32_16x16x32_bf16 v[48:51], v[56:59], v[72:75], v[96:99]
	v_mfma_f32_16x16x32_bf16 v[12:15], v[56:59], v[76:79], v[12:15]
	ds_read_b128 v[56:59], v137 offset:43584
	v_mfma_f32_16x16x32_bf16 v[24:27], v[60:63], v[64:67], v[24:27]
	ds_read_b128 v[64:67], v137 offset:48704
	v_mfma_f32_16x16x32_bf16 v[28:31], v[60:63], v[68:71], v[28:31]
	ds_read_b128 v[68:71], v138 offset:41024
	v_mfma_f32_16x16x32_bf16 v[36:39], v[60:63], v[72:75], v[36:39]
	ds_read_b128 v[72:75], v138 offset:43584
	v_mfma_f32_16x16x32_bf16 v[16:19], v[60:63], v[76:79], v[16:19]
	ds_read_b128 v[60:63], v137 offset:46144
	ds_read_b128 v[76:79], v138 offset:46144
	s_waitcnt lgkmcnt(0)
	s_barrier
	v_mfma_f32_16x16x32_bf16 v[80:83], v[52:55], v[68:71], v[80:83]
	v_mfma_f32_16x16x32_bf16 v[84:87], v[52:55], v[72:75], v[84:87]
	v_mfma_f32_16x16x32_bf16 v[88:91], v[52:55], v[76:79], v[88:91]
	v_mfma_f32_16x16x32_bf16 v[0:3], v[52:55], v[92:95], v[0:3]
	v_mov_b32_e32 v52, v211
	s_nop 0
	v_lshrrev_b32_e32 v54, 2, v52
	v_lshrrev_b32_e32 v53, 1, v52
	v_and_b32_e32 v54, 12, v54
	v_and_or_b32 v53, v53, s43, v54
	v_and_b32_e32 v52, 0x4f, v52
	v_mfma_f32_16x16x32_bf16 v[4:7], v[56:59], v[68:71], v[4:7]
	v_lshlrev_b32_e32 v52, 2, v52
	v_mul_lo_u32 v53, v53, s22
	v_add3_u32 v52, 0, v52, v53
	v_mfma_f32_16x16x32_bf16 v[20:23], v[56:59], v[72:75], v[20:23]
	v_add_u32_e32 v53, 0x400, v52
	ds_write2_b32 v52, v80, v84 offset1:16
	ds_write2_b32 v52, v81, v85 offset0:132 offset1:148
	ds_write2_b32 v53, v82, v86 offset0:8 offset1:24
	ds_write2_b32 v53, v83, v87 offset0:140 offset1:156
	ds_write2_b32 v52, v88, v0 offset0:32 offset1:48
	ds_write2_b32 v52, v89, v1 offset0:164 offset1:180
	ds_write2_b32 v53, v90, v2 offset0:40 offset1:56
	ds_write2_b32 v53, v91, v3 offset0:172 offset1:188
	v_mfma_f32_16x16x32_bf16 v[32:35], v[60:63], v[68:71], v[32:35]
	v_add_u32_e32 v0, 0x2000, v52
	v_add_u32_e32 v1, 0x2400, v52
	ds_write2_b32 v0, v4, v20 offset0:64 offset1:80
	ds_write2_b32 v0, v5, v21 offset0:196 offset1:212
	v_mfma_f32_16x16x32_bf16 v[44:47], v[60:63], v[72:75], v[44:47]
	v_add_u32_e32 v2, 0x4800, v52
	v_mfma_f32_16x16x32_bf16 v[40:43], v[56:59], v[76:79], v[40:43]
	v_mfma_f32_16x16x32_bf16 v[8:11], v[56:59], v[92:95], v[8:11]
	ds_write2_b32 v1, v6, v22 offset0:72 offset1:88
	ds_write2_b32 v1, v7, v23 offset0:204 offset1:220
	s_nop 5
	ds_write2_b32 v0, v40, v8 offset0:96 offset1:112
	ds_write2_b32 v0, v41, v9 offset0:228 offset1:244
	ds_write2_b32 v1, v42, v10 offset0:104 offset1:120
	ds_write2_b32 v1, v43, v11 offset0:236 offset1:252
	v_add_u32_e32 v0, 0x4000, v52
	v_mfma_f32_16x16x32_bf16 v[48:51], v[60:63], v[76:79], v[48:51]
	v_add_u32_e32 v1, 0x4400, v52
	ds_write2_b32 v0, v32, v44 offset0:128 offset1:144
	ds_write2_b32 v1, v33, v45 offset0:4 offset1:20
	ds_write2_b32 v1, v34, v46 offset0:136 offset1:152
	v_mfma_f32_16x16x32_bf16 v[12:15], v[60:63], v[92:95], v[12:15]
	ds_write2_b32 v2, v35, v47 offset0:12 offset1:28
	s_nop 6
	ds_write2_b32 v0, v48, v12 offset0:160 offset1:176
	ds_write2_b32 v1, v49, v13 offset0:36 offset1:52
	ds_write2_b32 v1, v50, v14 offset0:168 offset1:184
	ds_write2_b32 v2, v51, v15 offset0:44 offset1:60
	v_mfma_f32_16x16x32_bf16 v[24:27], v[64:67], v[68:71], v[24:27]
	v_add_u32_e32 v0, 0x6000, v52
	v_add_u32_e32 v1, 0x6400, v52
	v_add_u32_e32 v2, 0x6800, v52
	v_mfma_f32_16x16x32_bf16 v[28:31], v[64:67], v[72:75], v[28:31]
	v_mfma_f32_16x16x32_bf16 v[36:39], v[64:67], v[76:79], v[36:39]
	v_mfma_f32_16x16x32_bf16 v[16:19], v[64:67], v[92:95], v[16:19]
	s_nop 5
	ds_write2_b32 v0, v24, v28 offset0:192 offset1:208
	ds_write2_b32 v1, v25, v29 offset0:68 offset1:84
	ds_write2_b32 v1, v26, v30 offset0:200 offset1:216
	ds_write2_b32 v2, v27, v31 offset0:76 offset1:92
	ds_write2_b32 v0, v36, v16 offset0:224 offset1:240
	ds_write2_b32 v1, v37, v17 offset0:100 offset1:116
	ds_write2_b32 v1, v38, v18 offset0:232 offset1:248
	ds_write2_b32 v2, v39, v19 offset0:108 offset1:124
	v_mov_b32_e32 v0, v211
	s_waitcnt lgkmcnt(0)
	s_barrier
	s_nop 0
	v_lshlrev_b32_e32 v1, 3, v0
	v_and_b32_e32 v1, 0x78, v1
	v_ashrrev_i32_e32 v10, 4, v0
	v_lshlrev_b32_e32 v0, 2, v1
	v_lshlrev_b32_e32 v208, 1, v1
	v_mul_lo_u32 v1, v10, s22
	v_add3_u32 v11, 0, v0, v1
	ds_read_b128 v[0:3], v11
	ds_read_b128 v[4:7], v11 offset:16
	v_lshl_add_u64 v[8:9], s[0:1], 0, v[208:209]
	v_add_u32_e32 v12, 16, v10
	s_waitcnt lgkmcnt(1)
	v_cvt_pk_bf16_f32 v0, v0, v1
	v_cvt_pk_bf16_f32 v1, v2, v3
	s_waitcnt lgkmcnt(0)
	v_cvt_pk_bf16_f32 v2, v4, v5
	v_cvt_pk_bf16_f32 v3, v6, v7
	v_mad_i64_i32 v[4:5], s[0:1], v10, s11, v[8:9]
	global_store_dwordx4 v[4:5], v[0:3], off
	ds_read_b128 v[0:3], v11 offset:8448
	ds_read_b128 v[4:7], v11 offset:8464
	s_waitcnt lgkmcnt(1)
	v_cvt_pk_bf16_f32 v0, v0, v1
	v_cvt_pk_bf16_f32 v1, v2, v3
	s_waitcnt lgkmcnt(0)
	v_cvt_pk_bf16_f32 v2, v4, v5
	v_cvt_pk_bf16_f32 v3, v6, v7
	v_mad_i64_i32 v[4:5], s[0:1], v12, s11, v[8:9]
	global_store_dwordx4 v[4:5], v[0:3], off
	ds_read_b128 v[0:3], v11 offset:16896
	ds_read_b128 v[4:7], v11 offset:16912
	v_add_u32_e32 v12, 32, v10
	s_waitcnt lgkmcnt(1)
	v_cvt_pk_bf16_f32 v0, v0, v1
	v_cvt_pk_bf16_f32 v1, v2, v3
	s_waitcnt lgkmcnt(0)
	v_cvt_pk_bf16_f32 v2, v4, v5
	v_cvt_pk_bf16_f32 v3, v6, v7
	v_mad_i64_i32 v[4:5], s[0:1], v12, s11, v[8:9]
	global_store_dwordx4 v[4:5], v[0:3], off
	ds_read_b128 v[0:3], v11 offset:25344
	ds_read_b128 v[4:7], v11 offset:25360
	v_add_u32_e32 v12, 48, v10
	s_waitcnt lgkmcnt(1)
	v_cvt_pk_bf16_f32 v0, v0, v1
	v_cvt_pk_bf16_f32 v1, v2, v3
	s_waitcnt lgkmcnt(0)
	v_cvt_pk_bf16_f32 v2, v4, v5
	v_cvt_pk_bf16_f32 v3, v6, v7
	v_mad_i64_i32 v[4:5], s[0:1], v12, s11, v[8:9]
	global_store_dwordx4 v[4:5], v[0:3], off
	ds_read_b128 v[0:3], v11 offset:33792
	ds_read_b128 v[4:7], v11 offset:33808
	v_add_u32_e32 v12, 64, v10
	s_waitcnt lgkmcnt(1)
	v_cvt_pk_bf16_f32 v0, v0, v1
	v_cvt_pk_bf16_f32 v1, v2, v3
	s_waitcnt lgkmcnt(0)
	v_cvt_pk_bf16_f32 v2, v4, v5
	v_cvt_pk_bf16_f32 v3, v6, v7
	v_mad_i64_i32 v[4:5], s[0:1], v12, s11, v[8:9]
	global_store_dwordx4 v[4:5], v[0:3], off
	ds_read_b128 v[0:3], v11 offset:42240
	ds_read_b128 v[4:7], v11 offset:42256
	v_add_u32_e32 v12, 0x50, v10
	s_waitcnt lgkmcnt(1)
	v_cvt_pk_bf16_f32 v0, v0, v1
	v_cvt_pk_bf16_f32 v1, v2, v3
	s_waitcnt lgkmcnt(0)
	v_cvt_pk_bf16_f32 v2, v4, v5
	v_cvt_pk_bf16_f32 v3, v6, v7
	v_mad_i64_i32 v[4:5], s[0:1], v12, s11, v[8:9]
	global_store_dwordx4 v[4:5], v[0:3], off
	ds_read_b128 v[0:3], v11 offset:50688
	ds_read_b128 v[4:7], v11 offset:50704
	v_add_u32_e32 v12, 0x60, v10
	v_add_u32_e32 v10, 0x70, v10
	s_waitcnt lgkmcnt(1)
	v_cvt_pk_bf16_f32 v0, v0, v1
	v_cvt_pk_bf16_f32 v1, v2, v3
	s_waitcnt lgkmcnt(0)
	v_cvt_pk_bf16_f32 v2, v4, v5
	v_cvt_pk_bf16_f32 v3, v6, v7
	v_mad_i64_i32 v[4:5], s[0:1], v12, s11, v[8:9]
	global_store_dwordx4 v[4:5], v[0:3], off
	ds_read_b128 v[0:3], v11 offset:59136
	ds_read_b128 v[4:7], v11 offset:59152
	s_waitcnt lgkmcnt(1)
	v_cvt_pk_bf16_f32 v0, v0, v1
	v_cvt_pk_bf16_f32 v1, v2, v3
	s_waitcnt lgkmcnt(0)
	v_cvt_pk_bf16_f32 v2, v4, v5
	v_cvt_pk_bf16_f32 v3, v6, v7
	v_mad_i64_i32 v[4:5], s[0:1], v10, s11, v[8:9]
	global_store_dwordx4 v[4:5], v[0:3], off
	s_cbranch_scc0 .LBB0_313
